# RG-LRU conv/epilogue loads batched; gemm_wide compute phase hand-scheduled with LDS fragment reads one s-step ahead (A double-buffered, rotating B buffers)
# speedup vs baseline: 1.0990x; 1.0554x over previous
; #define MFMA32(a, b, c) __builtin_amdgcn_mfma_f32_32x32x16_bf16((a), (b), (c), 0, 0, 0)
; DI void gemm_wide(f32x16 (&acc)[2][4], const u16* __restrict__ A, int lda, const u16* __restrict__ Bt, int ldb, int K,
;                   char* smem) {
;     ...
;   for (int k0 = 0; k0 < K; k0 += 64) {
;     __syncthreads();
; #pragma unroll
;     for (int i = 0; i < 4; ++i) *(u32x4*)(As + (lr + 32 * i) * LS + lk) = ra[i];
; #pragma unroll
;     for (int i = 0; i < 8; ++i) *(u32x4*)(Bs + (lr + 32 * i) * LS + lk) = rb[i];
;     __syncthreads();
;     if (k0 + 64 < K) {
;       const int k1 = k0 + 64 + lk;
; #pragma unroll
;       for (int i = 0; i < 4; ++i) ra[i] = *(const u32x4*)(A + (size_t)(lr + 32 * i) * lda + k1);
; #pragma unroll
;       for (int i = 0; i < 8; ++i) rb[i] = *(const u32x4*)(Bt + (size_t)(lr + 32 * i) * ldb + k1);
;     }
; #pragma unroll
;     for (int s = 0; s < 4; ++s) {
;       bf16x8 a[2], b[4];
; #pragma unroll
;       for (int i = 0; i < 2; ++i) a[i] = *(const bf16x8*)(As + (wm * 64 + i * 32 + l31) * LS + s * 16 + hh * 8);
; #pragma unroll
;       for (int j = 0; j < 4; ++j) b[j] = *(const bf16x8*)(Bs + (wn * 128 + j * 32 + l31) * LS + s * 16 + hh * 8);
; #pragma unroll
;       for (int i = 0; i < 2; ++i)
; #pragma unroll
;         for (int j = 0; j < 4; ++j) acc[i][j] = MFMA32(a[i], b[j], acc[i][j]);
;     }
;   }
.LBB0_379:
	s_add_i32 s2, s2, 64
	v_lshl_add_u64 v[178:179], v[178:179], 0, s[50:51]
	v_lshl_add_u64 v[180:181], v[180:181], 0, s[50:51]
	s_andn2_b64 vcc, exec, s[12:13]
	ds_read_b128 v[236:239], v185 offset:32
	ds_read_b128 v[224:227], v186 offset:18464
	ds_read_b128 v[248:251], v185 offset:4640
	ds_read_b128 v[230:233], v186 offset:23072
	s_waitcnt lgkmcnt(8)
	v_mfma_f32_32x32x16_bf16 v[114:129], v[188:191], v[192:195], v[114:129]
	s_waitcnt lgkmcnt(7)
	v_mfma_f32_32x32x16_bf16 v[50:65], v[244:247], v[192:195], v[50:65]
	ds_read_b128 v[192:195], v186 offset:27680
	s_waitcnt lgkmcnt(7)
	v_mfma_f32_32x32x16_bf16 v[98:113], v[188:191], v[200:203], v[98:113]
	v_mfma_f32_32x32x16_bf16 v[34:49], v[244:247], v[200:203], v[34:49]
	ds_read_b128 v[200:203], v186 offset:32288
	s_waitcnt lgkmcnt(7)
	v_mfma_f32_32x32x16_bf16 v[82:97], v[188:191], v[204:207], v[82:97]
	v_mfma_f32_32x32x16_bf16 v[18:33], v[244:247], v[204:207], v[18:33]
	s_waitcnt lgkmcnt(6)
	v_mfma_f32_32x32x16_bf16 v[66:81], v[188:191], v[208:211], v[66:81]
	v_mfma_f32_32x32x16_bf16 v[2:17], v[244:247], v[208:211], v[2:17]
	ds_read_b128 v[188:191], v185 offset:64
	ds_read_b128 v[204:207], v186 offset:18496
	ds_read_b128 v[244:247], v185 offset:4672
	ds_read_b128 v[208:211], v186 offset:23104
	s_waitcnt lgkmcnt(8)
	v_mfma_f32_32x32x16_bf16 v[114:129], v[236:239], v[224:227], v[114:129]
	s_waitcnt lgkmcnt(7)
	v_mfma_f32_32x32x16_bf16 v[50:65], v[248:251], v[224:227], v[50:65]
	ds_read_b128 v[224:227], v186 offset:27712
	s_waitcnt lgkmcnt(7)
	v_mfma_f32_32x32x16_bf16 v[98:113], v[236:239], v[230:233], v[98:113]
	v_mfma_f32_32x32x16_bf16 v[34:49], v[248:251], v[230:233], v[34:49]
	ds_read_b128 v[230:233], v186 offset:32320
	s_waitcnt lgkmcnt(7)
	v_mfma_f32_32x32x16_bf16 v[82:97], v[236:239], v[192:195], v[82:97]
	v_mfma_f32_32x32x16_bf16 v[18:33], v[248:251], v[192:195], v[18:33]
	s_waitcnt lgkmcnt(6)
	v_mfma_f32_32x32x16_bf16 v[66:81], v[236:239], v[200:203], v[66:81]
	v_mfma_f32_32x32x16_bf16 v[2:17], v[248:251], v[200:203], v[2:17]
	ds_read_b128 v[236:239], v185 offset:96
	ds_read_b128 v[192:195], v186 offset:18528
	ds_read_b128 v[248:251], v185 offset:4704
	ds_read_b128 v[200:203], v186 offset:23136
	s_waitcnt lgkmcnt(8)
	v_mfma_f32_32x32x16_bf16 v[114:129], v[188:191], v[204:207], v[114:129]
	s_waitcnt lgkmcnt(7)
	v_mfma_f32_32x32x16_bf16 v[50:65], v[244:247], v[204:207], v[50:65]
	ds_read_b128 v[204:207], v186 offset:27744
	s_waitcnt lgkmcnt(7)
	v_mfma_f32_32x32x16_bf16 v[98:113], v[188:191], v[208:211], v[98:113]
	v_mfma_f32_32x32x16_bf16 v[34:49], v[244:247], v[208:211], v[34:49]
	ds_read_b128 v[208:211], v186 offset:32352
	s_waitcnt lgkmcnt(7)
	v_mfma_f32_32x32x16_bf16 v[82:97], v[188:191], v[224:227], v[82:97]
	v_mfma_f32_32x32x16_bf16 v[18:33], v[244:247], v[224:227], v[18:33]
	s_waitcnt lgkmcnt(6)
	v_mfma_f32_32x32x16_bf16 v[66:81], v[188:191], v[230:233], v[66:81]
	v_mfma_f32_32x32x16_bf16 v[2:17], v[244:247], v[230:233], v[2:17]
	s_waitcnt lgkmcnt(4)
	v_mfma_f32_32x32x16_bf16 v[114:129], v[236:239], v[192:195], v[114:129]
	s_waitcnt lgkmcnt(3)
	v_mfma_f32_32x32x16_bf16 v[50:65], v[248:251], v[192:195], v[50:65]
	s_waitcnt lgkmcnt(2)
	v_mfma_f32_32x32x16_bf16 v[98:113], v[236:239], v[200:203], v[98:113]
	v_mfma_f32_32x32x16_bf16 v[34:49], v[248:251], v[200:203], v[34:49]
	s_waitcnt lgkmcnt(1)
	v_mfma_f32_32x32x16_bf16 v[82:97], v[236:239], v[204:207], v[82:97]
	v_mfma_f32_32x32x16_bf16 v[18:33], v[248:251], v[204:207], v[18:33]
	s_waitcnt lgkmcnt(0)
	v_mfma_f32_32x32x16_bf16 v[66:81], v[236:239], v[208:211], v[66:81]
	v_mfma_f32_32x32x16_bf16 v[2:17], v[248:251], v[208:211], v[2:17]
	s_cbranch_vccz .LBB0_382
.LBB0_380:
	s_cmpk_gt_u32 s2, 0x3bf
	s_cselect_b64 s[12:13], -1, 0
	s_and_b64 vcc, exec, s[12:13]
	s_waitcnt vmcnt(63) expcnt(7) lgkmcnt(15)
	s_barrier
	s_waitcnt vmcnt(11)
	ds_write_b128 v184, v[130:133]
	s_waitcnt vmcnt(10)
	ds_write_b128 v184, v[134:137] offset:4608
	s_waitcnt vmcnt(9)
	ds_write_b128 v184, v[138:141] offset:9216
	s_waitcnt vmcnt(8)
	ds_write_b128 v184, v[142:145] offset:13824
	s_waitcnt vmcnt(7)
	ds_write_b128 v184, v[146:149] offset:18432
	s_waitcnt vmcnt(6)
	ds_write_b128 v184, v[150:153] offset:23040
	s_waitcnt vmcnt(5)
	ds_write_b128 v184, v[154:157] offset:27648
	s_waitcnt vmcnt(4)
	ds_write_b128 v184, v[158:161] offset:32256
	s_waitcnt vmcnt(3)
	ds_write_b128 v184, v[162:165] offset:36864
	s_waitcnt vmcnt(2)
	ds_write_b128 v184, v[166:169] offset:41472
	s_waitcnt vmcnt(1)
	ds_write_b128 v184, v[170:173] offset:46080
	s_waitcnt vmcnt(0)
	ds_write_b128 v184, v[174:177] offset:50688
	s_waitcnt lgkmcnt(0)
	s_barrier
	ds_read_b128 v[188:191], v185
	ds_read_b128 v[192:195], v186 offset:18432
	ds_read_b128 v[244:247], v185 offset:4608
	ds_read_b128 v[200:203], v186 offset:23040
	ds_read_b128 v[204:207], v186 offset:27648
	ds_read_b128 v[208:211], v186 offset:32256
	s_cbranch_vccnz .LBB0_379
	v_lshl_add_u64 v[138:139], v[180:181], 0, v[198:199]
	v_add_co_u32_e32 v134, vcc, 0x10000, v138
	v_lshl_add_u64 v[170:171], v[178:179], 0, v[198:199]
	s_nop 0
	v_addc_co_u32_e32 v135, vcc, 0, v139, vcc
	v_add_co_u32_e32 v140, vcc, 0x20000, v138
	global_load_dwordx4 v[130:133], v[138:139], off offset:128
	s_nop 0
	global_load_dwordx4 v[134:137], v[134:135], off offset:128
	v_addc_co_u32_e32 v141, vcc, 0, v139, vcc
	v_add_co_u32_e32 v142, vcc, 0x30000, v138
	s_nop 1
	v_addc_co_u32_e32 v143, vcc, 0, v139, vcc
	v_add_co_u32_e32 v146, vcc, 0xd150000, v170
	global_load_dwordx4 v[138:141], v[140:141], off offset:128
	s_nop 0
	global_load_dwordx4 v[142:145], v[142:143], off offset:128
	v_addc_co_u32_e32 v147, vcc, 0, v171, vcc
	v_add_co_u32_e32 v150, vcc, 0xd160000, v170
	s_nop 1
	v_addc_co_u32_e32 v151, vcc, 0, v171, vcc
	v_add_co_u32_e32 v154, vcc, 0xd170000, v170
	global_load_dwordx4 v[146:149], v[146:147], off offset:128
	s_nop 0
	global_load_dwordx4 v[150:153], v[150:151], off offset:128
	v_addc_co_u32_e32 v155, vcc, 0, v171, vcc
	v_add_co_u32_e32 v158, vcc, 0xd180000, v170
	s_nop 1
	v_addc_co_u32_e32 v159, vcc, 0, v171, vcc
	v_add_co_u32_e32 v162, vcc, 0xd190000, v170
	global_load_dwordx4 v[154:157], v[154:155], off offset:128
	s_nop 0
	global_load_dwordx4 v[158:161], v[158:159], off offset:128
	v_addc_co_u32_e32 v163, vcc, 0, v171, vcc
	v_add_co_u32_e32 v166, vcc, 0xd1a0000, v170
	s_nop 1
	v_addc_co_u32_e32 v167, vcc, 0, v171, vcc
	v_add_co_u32_e32 v172, vcc, 0xd1b0000, v170
	global_load_dwordx4 v[162:165], v[162:163], off offset:128
	s_nop 0
	global_load_dwordx4 v[166:169], v[166:167], off offset:128
	v_addc_co_u32_e32 v173, vcc, 0, v171, vcc
	v_add_co_u32_e32 v174, vcc, 0xd1c0000, v170
	s_nop 1
	v_addc_co_u32_e32 v175, vcc, 0, v171, vcc
	global_load_dwordx4 v[170:173], v[172:173], off offset:128
	s_nop 0
	global_load_dwordx4 v[174:177], v[174:175], off offset:128
	s_branch .LBB0_379

; DI float bf2f(u16 v) { return __uint_as_float(((unsigned)v) << 16); }
;     ...
;     const int c = tid & 63, tq = tid >> 6, cg = g * 64 + c;
;     const float w0 = p->lru_conv_w[(l * 4 + 0) * 512 + cg], w1 = p->lru_conv_w[(l * 4 + 1) * 512 + cg];
;     const float w2 = p->lru_conv_w[(l * 4 + 2) * 512 + cg], w3 = p->lru_conv_w[(l * 4 + 3) * 512 + cg];
;     const float bias = p->lru_conv_b[l * 512 + cg];
;     auto ld = [&](int tt) -> float {
;       int tp = tpos0 + tt;
;       return (tp >= 0 && tp < seglen) ? bf2f(Zlx[(size_t)(base + tt) * 512 + cg]) : 0.f;
;     };
;     const int t0 = tq * 16;
;     float xv[19];
; #pragma unroll
;     for (int e = 0; e < 19; ++e) xv[e] = ld(t0 - 2 + e);
.LBB0_523:
	s_load_dwordx2 s[6:7], s[8:9], 0x130
	s_waitcnt lgkmcnt(0)
	s_barrier
	s_load_dwordx4 s[24:27], s[8:9], 0x68
	s_and_b32 s5, s4, 7
	v_and_b32_e32 v10, 63, v66
	s_lshl_b32 s4, s5, 6
	v_or_b32_e32 v11, s4, v10
	s_waitcnt lgkmcnt(0)
	v_mov_b32_e32 v2, s24
	v_mov_b32_e32 v3, s25
	v_or_b32_e32 v198, s77, v11
	v_lshl_add_u64 v[2:3], v[198:199], 2, v[2:3]
	v_add_co_u32_e32 v14, vcc, s47, v2
	v_mov_b32_e32 v12, s26
	v_mov_b32_e32 v13, s27
	v_addc_co_u32_e32 v15, vcc, 0, v3, vcc
	global_load_dword v5, v[2:3], off
	global_load_dword v8, v[2:3], off offset:2048
	global_load_dword v7, v[14:15], off
	global_load_dword v6, v[14:15], off offset:2048
	v_or_b32_e32 v198, s80, v11
	v_lshl_add_u64 v[2:3], v[198:199], 2, v[12:13]
	global_load_dword v9, v[2:3], off
	v_ashrrev_i32_e32 v4, 6, v66
	v_lshlrev_b32_e32 v14, 4, v4
	v_lshlrev_b32_e32 v31, 1, v11
	v_add_u32_e32 v38, s12, v14
	s_add_u32 s10, s6, 0x3850000
	s_addc_u32 s11, s7, 0
	v_lshl_add_u32 v31, v38, 10, v31
	v_add_u32_e32 v34, 0x1000, v31
	v_add_u32_e32 v35, 0x2000, v31
	v_add_u32_e32 v36, 0x3000, v31
	v_add_u32_e32 v37, 0x4000, v31
	global_load_ushort v12, v31, s[10:11] offset:-2048
	global_load_ushort v11, v31, s[10:11] offset:-1024
	global_load_ushort v15, v31, s[10:11]
	global_load_ushort v13, v31, s[10:11] offset:1024
	global_load_ushort v18, v31, s[10:11] offset:2048
	global_load_ushort v16, v31, s[10:11] offset:3072
	global_load_ushort v20, v34, s[10:11]
	global_load_ushort v19, v34, s[10:11] offset:1024
	global_load_ushort v22, v34, s[10:11] offset:2048
	global_load_ushort v21, v34, s[10:11] offset:3072
	global_load_ushort v24, v35, s[10:11]
	global_load_ushort v23, v35, s[10:11] offset:1024
	global_load_ushort v26, v35, s[10:11] offset:2048
	global_load_ushort v25, v35, s[10:11] offset:3072
	global_load_ushort v28, v36, s[10:11]
	global_load_ushort v27, v36, s[10:11] offset:1024
	global_load_ushort v30, v36, s[10:11] offset:2048
	global_load_ushort v29, v36, s[10:11] offset:3072
	global_load_ushort v39, v37, s[10:11]
	v_or_b32_e32 v17, 1, v14
	v_add_u32_e32 v38, s13, v14
	v_add_u32_e32 v40, -2, v38
	s_waitcnt vmcnt(0)
	v_cmp_gt_u32_e32 vcc, s15, v40
	v_lshlrev_b32_e32 v12, 16, v12
	v_add_u32_e32 v41, -1, v38
	v_cndmask_b32_e32 v12, 0, v12, vcc
	v_cmp_gt_u32_e32 vcc, s15, v41
	v_lshlrev_b32_e32 v11, 16, v11
	v_add_u32_e32 v40, 0, v38
	v_cndmask_b32_e32 v11, 0, v11, vcc
	v_cmp_gt_u32_e32 vcc, s15, v40
	v_lshlrev_b32_e32 v15, 16, v15
	v_add_u32_e32 v41, 1, v38
	v_cndmask_b32_e32 v15, 0, v15, vcc
	v_cmp_gt_u32_e32 vcc, s15, v41
	v_lshlrev_b32_e32 v13, 16, v13
	v_add_u32_e32 v40, 2, v38
	v_cndmask_b32_e32 v13, 0, v13, vcc
	v_cmp_gt_u32_e32 vcc, s15, v40
	v_lshlrev_b32_e32 v18, 16, v18
	v_add_u32_e32 v41, 3, v38
	v_cndmask_b32_e32 v18, 0, v18, vcc
	v_cmp_gt_u32_e32 vcc, s15, v41
	v_lshlrev_b32_e32 v16, 16, v16
	v_add_u32_e32 v40, 4, v38
	v_cndmask_b32_e32 v16, 0, v16, vcc
	v_cmp_gt_u32_e32 vcc, s15, v40
	v_lshlrev_b32_e32 v20, 16, v20
	v_add_u32_e32 v41, 5, v38
	v_cndmask_b32_e32 v20, 0, v20, vcc
	v_cmp_gt_u32_e32 vcc, s15, v41
	v_lshlrev_b32_e32 v19, 16, v19
	v_add_u32_e32 v40, 6, v38
	v_cndmask_b32_e32 v19, 0, v19, vcc
	v_cmp_gt_u32_e32 vcc, s15, v40
	v_lshlrev_b32_e32 v22, 16, v22
	v_add_u32_e32 v41, 7, v38
	v_cndmask_b32_e32 v22, 0, v22, vcc
	v_cmp_gt_u32_e32 vcc, s15, v41
	v_lshlrev_b32_e32 v21, 16, v21
	v_add_u32_e32 v40, 8, v38
	v_cndmask_b32_e32 v21, 0, v21, vcc
	v_cmp_gt_u32_e32 vcc, s15, v40
	v_lshlrev_b32_e32 v24, 16, v24
	v_add_u32_e32 v41, 9, v38
	v_cndmask_b32_e32 v24, 0, v24, vcc
	v_cmp_gt_u32_e32 vcc, s15, v41
	v_lshlrev_b32_e32 v23, 16, v23
	v_add_u32_e32 v40, 10, v38
	v_cndmask_b32_e32 v23, 0, v23, vcc
	v_cmp_gt_u32_e32 vcc, s15, v40
	v_lshlrev_b32_e32 v26, 16, v26
	v_add_u32_e32 v41, 11, v38
	v_cndmask_b32_e32 v26, 0, v26, vcc
	v_cmp_gt_u32_e32 vcc, s15, v41
	v_lshlrev_b32_e32 v25, 16, v25
	v_add_u32_e32 v40, 12, v38
	v_cndmask_b32_e32 v25, 0, v25, vcc
	v_cmp_gt_u32_e32 vcc, s15, v40
	v_lshlrev_b32_e32 v28, 16, v28
	v_add_u32_e32 v41, 13, v38
	v_cndmask_b32_e32 v28, 0, v28, vcc
	v_cmp_gt_u32_e32 vcc, s15, v41
	v_lshlrev_b32_e32 v27, 16, v27
	v_add_u32_e32 v40, 14, v38
	v_cndmask_b32_e32 v27, 0, v27, vcc
	v_cmp_gt_u32_e32 vcc, s15, v40
	v_lshlrev_b32_e32 v30, 16, v30
	v_add_u32_e32 v41, 15, v38
	v_cndmask_b32_e32 v30, 0, v30, vcc
	v_cmp_gt_u32_e32 vcc, s15, v41
	v_lshlrev_b32_e32 v29, 16, v29
	v_add_u32_e32 v40, 16, v38
	v_cndmask_b32_e32 v29, 0, v29, vcc
	v_cmp_gt_u32_e32 vcc, s15, v40
	v_lshlrev_b32_e32 v39, 16, v39
	s_nop 0
	v_cndmask_b32_e32 v39, 0, v39, vcc
	v_mov_b32_e32 v14, v39
	v_lshlrev_b32_e32 v2, 2, v10
	v_lshlrev_b32_e32 v3, 1, v10
	v_lshrrev_b32_e32 v74, 5, v10
	v_sub_u32_e32 v10, v2, v3
	s_waitcnt vmcnt(3)
	v_mul_f32_e32 v3, v8, v11
	v_fmac_f32_e32 v3, v5, v12
	s_waitcnt vmcnt(2)
	v_fmac_f32_e32 v3, v7, v15
	s_waitcnt vmcnt(1)
	v_fmac_f32_e32 v3, v6, v13
	s_waitcnt vmcnt(0)
;     ...
; #pragma unroll
;     for (int tt = 0; tt < 16; ++tt) {
;       const float y = w0 * xv[tt] + w1 * xv[tt + 1] + w2 * xv[tt + 2] + w3 * xv[tt + 3] + bias;
;       uf[(t0 + tt) * 65 + c] = y;
;       Au[(t0 + tt) * 72 + c] = f2bf(y);
;     }
;   }
;   if (pass == 3) {
;     const int part = tid >> 7, dir = (tid >> 6) & 1, c = tid & 63, cg = g * 64 + c;
;     const f32x2* ag = agg + ((size_t)(b * 68) * 2 + dir) * 512 + cg;
;     f32x2 ab[34];
; #pragma unroll
;     for (int e = 0; e < 34; ++e) {
;       const int sl = part * 34 + e;
;       int ch; bool valid;
;       if (dir == 0) { ch = sl; valid = sl < j; }
;       else { ch = (sl < 4) ? (3 - sl) : (71 - sl); valid = (j < 4) ? (sl < 4 && ch > j) : (sl < 4 || ch > j); }
;       ab[e] = valid ? ag[(size_t)ch * 1024] : mkf2(1.f, 0.f);
;     }
;     float A = 1.f, Bv = 0.f;
; #pragma unroll
;     for (int e = 0; e < 34; ++e) { A *= ab[e].x; Bv = ab[e].x * Bv + ab[e].y; }
;     ((f32x2*)carry)[(part * 2 + dir) * 64 + c] = mkf2(A, Bv);
;   }
;   __syncthreads();
;   const int th = w >> 1, chh = w & 1;
;   f32x16 acc[4];
; #pragma unroll
;   for (int m = 0; m < 4; ++m) zero_acc(acc[m]);
;   const u16* Wl = (const u16*)(p->ws + OFF_W) + W_LRU + (size_t)g * 256 * 64;
	v_add_f32_e32 v3, v9, v3
	s_movk_i32 s10, 0x1040
	v_mad_u64_u32 v[32:33], s[10:11], v4, s10, v[2:3]
	s_movk_i32 s10, 0x900
	ds_write_b32 v32, v3 offset:9216
	v_cvt_pk_bf16_f32 v3, v3, s0
	v_mad_u64_u32 v[32:33], s[10:11], v4, s10, v[10:11]
	ds_write_b16 v32, v3
	v_mul_f32_e32 v3, v8, v15
	v_fmac_f32_e32 v3, v5, v11
	v_fmac_f32_e32 v3, v7, v13
	v_fmac_f32_e32 v3, v6, v18
	v_add_f32_e32 v12, v9, v3
	v_mad_u64_u32 v[2:3], s[10:11], v17, s54, v[2:3]
	v_cvt_pk_bf16_f32 v3, v12, s0
	v_mad_u64_u32 v[10:11], s[10:11], v17, s60, v[10:11]
	ds_write_b16 v10, v3
	v_mul_f32_e32 v3, v8, v13
	v_fmac_f32_e32 v3, v5, v15
	v_fmac_f32_e32 v3, v7, v18
	v_fmac_f32_e32 v3, v6, v16
	v_add_f32_e32 v3, v9, v3
	v_add_u32_e32 v11, 0x2400, v2
	ds_write2_b32 v11, v12, v3 offset1:65
	v_cvt_pk_bf16_f32 v3, v3, s0
	ds_write_b16 v10, v3 offset:144
	v_mul_f32_e32 v3, v8, v18
	v_fmac_f32_e32 v3, v5, v13
	v_fmac_f32_e32 v3, v7, v16
	v_fmac_f32_e32 v3, v6, v20
	v_add_f32_e32 v3, v9, v3
	v_cvt_pk_bf16_f32 v12, v3, s0
	ds_write_b16 v10, v12 offset:288
	v_mul_f32_e32 v12, v8, v16
	v_fmac_f32_e32 v12, v5, v18
	v_fmac_f32_e32 v12, v7, v20
	v_fmac_f32_e32 v12, v6, v19
	v_add_f32_e32 v12, v9, v12
	ds_write2_b32 v11, v3, v12 offset0:130 offset1:195
	v_cvt_pk_bf16_f32 v3, v12, s0
	ds_write_b16 v10, v3 offset:432
	v_mul_f32_e32 v3, v8, v20
	v_fmac_f32_e32 v3, v5, v16
	v_fmac_f32_e32 v3, v7, v19
	v_fmac_f32_e32 v3, v6, v22
	v_add_f32_e32 v3, v9, v3
	v_cvt_pk_bf16_f32 v11, v3, s0
	ds_write_b16 v10, v11 offset:576
	v_mul_f32_e32 v11, v8, v19
	v_fmac_f32_e32 v11, v5, v20
	v_fmac_f32_e32 v11, v7, v22
	v_fmac_f32_e32 v11, v6, v21
	v_add_f32_e32 v11, v9, v11
	v_add_u32_e32 v12, 0x2800, v2
	ds_write2_b32 v12, v3, v11 offset0:4 offset1:69
	v_cvt_pk_bf16_f32 v3, v11, s0
	ds_write_b16 v10, v3 offset:720
	v_mul_f32_e32 v3, v8, v22
	v_fmac_f32_e32 v3, v5, v19
	v_fmac_f32_e32 v3, v7, v21
	v_fmac_f32_e32 v3, v6, v24
	v_add_f32_e32 v3, v9, v3
	v_cvt_pk_bf16_f32 v11, v3, s0
	ds_write_b16 v10, v11 offset:864
	v_mul_f32_e32 v11, v8, v21
	v_fmac_f32_e32 v11, v5, v22
	v_fmac_f32_e32 v11, v7, v24
	v_fmac_f32_e32 v11, v6, v23
	v_add_f32_e32 v11, v9, v11
	ds_write2_b32 v12, v3, v11 offset0:134 offset1:199
	v_cvt_pk_bf16_f32 v3, v11, s0
	ds_write_b16 v10, v3 offset:1008
	v_mul_f32_e32 v3, v8, v24
	v_fmac_f32_e32 v3, v5, v21
	v_fmac_f32_e32 v3, v7, v23
	v_fmac_f32_e32 v3, v6, v26
	v_add_f32_e32 v3, v9, v3
	v_cvt_pk_bf16_f32 v11, v3, s0
	ds_write_b16 v10, v11 offset:1152
	v_mul_f32_e32 v11, v8, v23
	v_fmac_f32_e32 v11, v5, v24
	v_fmac_f32_e32 v11, v7, v26
	v_fmac_f32_e32 v11, v6, v25
	v_add_f32_e32 v11, v9, v11
	v_add_u32_e32 v12, 0x2c00, v2
	ds_write2_b32 v12, v3, v11 offset0:8 offset1:73
	v_cvt_pk_bf16_f32 v3, v11, s0
	ds_write_b16 v10, v3 offset:1296
	v_mul_f32_e32 v3, v8, v26
	v_fmac_f32_e32 v3, v5, v23
	v_fmac_f32_e32 v3, v7, v25
	v_fmac_f32_e32 v3, v6, v28
	v_add_f32_e32 v3, v9, v3
	v_cvt_pk_bf16_f32 v11, v3, s0
	ds_write_b16 v10, v11 offset:1440
	v_mul_f32_e32 v11, v8, v25
	v_fmac_f32_e32 v11, v5, v26
	v_fmac_f32_e32 v11, v7, v28
	v_fmac_f32_e32 v11, v6, v27
	v_add_f32_e32 v11, v9, v11
	ds_write2_b32 v12, v3, v11 offset0:138 offset1:203
	v_cvt_pk_bf16_f32 v3, v11, s0
	ds_write_b16 v10, v3 offset:1584
	v_mul_f32_e32 v3, v8, v28
	v_fmac_f32_e32 v3, v5, v25
	v_fmac_f32_e32 v3, v7, v27
	v_fmac_f32_e32 v3, v6, v30
	v_add_f32_e32 v3, v9, v3
	v_cvt_pk_bf16_f32 v11, v3, s0
	ds_write_b16 v10, v11 offset:1728
	v_mul_f32_e32 v11, v8, v27
	v_fmac_f32_e32 v11, v5, v28
	v_fmac_f32_e32 v11, v7, v30
	v_fmac_f32_e32 v11, v6, v29
	v_add_f32_e32 v11, v9, v11
	v_add_u32_e32 v12, 0x3000, v2
	ds_write2_b32 v12, v3, v11 offset0:12 offset1:77
	v_cvt_pk_bf16_f32 v3, v11, s0
	ds_write_b16 v10, v3 offset:1872
	v_mul_f32_e32 v3, v8, v30
	v_fmac_f32_e32 v3, v5, v27
	v_fmac_f32_e32 v3, v7, v29
	v_fmac_f32_e32 v3, v6, v14
	v_add_f32_e32 v3, v9, v3
	s_lshl_b32 s5, s5, 15
	ds_write_b32 v2, v3 offset:12856
	v_cvt_pk_bf16_f32 v2, v3, s0
	s_add_u32 s10, s6, s5
	v_ashrrev_i32_e32 v78, 2, v66
	s_movk_i32 s5, 0xffe0
	ds_write_b16 v10, v2 offset:2016
	v_bfi_b32 v2, s5, v78, v66
	v_lshlrev_b32_e32 v198, 4, v74
	v_and_b32_e32 v31, 31, v66
	s_addc_u32 s11, s7, 0
	v_mad_u64_u32 v[72:73], s[12:13], v2, s60, v[198:199]
	v_lshlrev_b32_e32 v2, 5, v4
	v_lshl_add_u64 v[96:97], s[10:11], 0, v[198:199]
	s_mov_b64 s[10:11], 0xe3e0000
	v_and_or_b32 v77, v2, 32, v31
	v_lshl_add_u64 v[14:15], v[96:97], 0, s[10:11]
	v_lshlrev_b32_e32 v198, 7, v77
	v_lshl_add_u64 v[92:93], v[14:15], 0, v[198:199]
	s_waitcnt lgkmcnt(0)
	s_barrier
; #define MFMA32(a, b, c) __builtin_amdgcn_mfma_f32_32x32x16_bf16((a), (b), (c), 0, 0, 0)
;     ...
; #pragma unroll
;   for (int s = 0; s < 4; ++s) {
;     bf16x8 a = *(const bf16x8*)(Au + (th * 32 + l31) * 72 + s * 16 + hh * 8);
; #pragma unroll
;     for (int m = 0; m < 4; ++m) {
;       bf16x8 bb = *(const bf16x8*)(Wl + (size_t)(m * 64 + chh * 32 + l31) * 64 + s * 16 + hh * 8);
;       acc[m] = MFMA32(a, bb, acc[m]);
;     }
;   }
;   asm volatile("s_nop 15\n\ts_nop 15" ::: "memory");
;   const int cl = chh * 32 + l31, cg = g * 64 + cl;
;   float hsum[16];
; #pragma unroll
;   for (int dir = 0; dir < 2; ++dir) {
;     const float ba = p->lru_ba[(l * 2 + dir) * 512 + cg], bx = p->lru_bx[(l * 2 + dir) * 512 + cg];
;     const float lam = p->lru_lam[(l * 2 + dir) * 512 + cg];
;     const float ex = __expf(-lam);
;     const float sp = (ex < 0.03f) ? ex * (1.f - ex * (0.5f - ex * (0.33333334f - 0.25f * ex))) : __logf(1.f + ex);
	global_load_dwordx4 v[2:5], v[92:93], off
	global_load_dwordx4 v[80:83], v[92:93], off offset:32
	ds_read_b128 v[6:9], v72
	ds_read_b128 v[68:71], v72 offset:32
	v_or_b32_e32 v98, 0x2000, v198
	v_mov_b32_e32 v99, v199
	v_or_b32_e32 v100, 0x4000, v198
	v_mov_b32_e32 v101, v199
	v_lshl_add_u64 v[10:11], v[14:15], 0, v[98:99]
	global_load_dwordx4 v[10:13], v[10:11], off
	s_mov_b64 s[10:11], 0xe3e0020
	v_or_b32_e32 v198, 0x6000, v198
	v_lshl_add_u64 v[88:89], v[96:97], 0, s[10:11]
	s_mov_b64 s[10:11], 0xe3e0040
	v_lshl_add_u64 v[102:103], v[96:97], 0, s[10:11]
	s_mov_b64 s[10:11], 0xe3e0060
	v_lshl_add_u64 v[96:97], v[96:97], 0, s[10:11]
	s_or_b32 s5, s4, s74
	s_waitcnt vmcnt(2) lgkmcnt(1)
	v_mfma_f32_32x32x16_bf16 v[50:65], v[6:9], v[2:5], 0
	v_lshl_add_u64 v[2:3], v[14:15], 0, v[100:101]
	global_load_dwordx4 v[2:5], v[2:3], off
	s_waitcnt vmcnt(1)
	v_mfma_f32_32x32x16_bf16 v[34:49], v[6:9], v[10:13], 0
	v_lshl_add_u64 v[10:11], v[88:89], 0, v[98:99]
	global_load_dwordx4 v[84:87], v[10:11], off
	s_waitcnt vmcnt(1)
	v_mfma_f32_32x32x16_bf16 v[18:33], v[6:9], v[2:5], 0
	v_lshl_add_u64 v[2:3], v[14:15], 0, v[198:199]
	global_load_dwordx4 v[2:5], v[2:3], off
	s_waitcnt lgkmcnt(0)
	v_mfma_f32_32x32x16_bf16 v[50:65], v[68:71], v[80:83], v[50:65]
	v_lshl_add_u64 v[80:81], v[88:89], 0, v[100:101]
	global_load_dwordx4 v[80:83], v[80:81], off
	s_waitcnt vmcnt(2)
	v_mfma_f32_32x32x16_bf16 v[34:49], v[68:71], v[84:87], v[34:49]
	v_lshl_add_u64 v[84:85], v[88:89], 0, v[198:199]
	global_load_dwordx4 v[84:87], v[84:85], off
	ds_read_b128 v[88:91], v72 offset:96
	s_waitcnt vmcnt(1)
	v_mfma_f32_32x32x16_bf16 v[18:33], v[68:71], v[80:83], v[18:33]
	global_load_dwordx4 v[80:83], v[92:93], off offset:64
	s_nop 0
	global_load_dwordx4 v[92:95], v[92:93], off offset:96
	v_mfma_f32_32x32x16_bf16 v[2:17], v[6:9], v[2:5], 0
	s_waitcnt vmcnt(2)
	v_mfma_f32_32x32x16_bf16 v[2:17], v[68:71], v[84:87], v[2:17]
	ds_read_b128 v[68:71], v72 offset:64
	v_lshl_add_u64 v[84:85], v[102:103], 0, v[98:99]
	v_lshl_add_u64 v[72:73], v[102:103], 0, v[100:101]
	global_load_dwordx4 v[84:87], v[84:85], off
	s_waitcnt vmcnt(2) lgkmcnt(0)
	v_mfma_f32_32x32x16_bf16 v[50:65], v[68:71], v[80:83], v[50:65]
	global_load_dwordx4 v[80:83], v[72:73], off
	v_lshl_add_u64 v[72:73], v[102:103], 0, v[198:199]
	s_waitcnt vmcnt(1)
	v_mfma_f32_32x32x16_bf16 v[34:49], v[68:71], v[84:87], v[34:49]
	s_waitcnt vmcnt(0)
	v_mfma_f32_32x32x16_bf16 v[18:33], v[68:71], v[80:83], v[18:33]
	global_load_dwordx4 v[80:83], v[72:73], off
	v_lshl_add_u64 v[72:73], v[96:97], 0, v[98:99]
	global_load_dwordx4 v[84:87], v[72:73], off
	s_waitcnt vmcnt(1)
	v_mfma_f32_32x32x16_bf16 v[2:17], v[68:71], v[80:83], v[2:17]
	v_lshl_add_u64 v[68:69], v[96:97], 0, v[100:101]
	global_load_dwordx4 v[70:73], v[68:69], off
	v_lshl_add_u64 v[68:69], v[96:97], 0, v[198:199]
	global_load_dwordx4 v[80:83], v[68:69], off
	s_nop 15
	s_nop 15
	s_load_dwordx4 s[24:27], s[8:9], 0x90
	v_or_b32_e32 v198, s5, v77
	s_waitcnt vmcnt(2)
	v_mfma_f32_32x32x16_bf16 v[34:49], v[88:91], v[84:87], v[34:49]
	v_lshlrev_b64 v[84:85], 2, v[198:199]
	s_load_dwordx2 s[8:9], s[8:9], 0x80
	s_waitcnt lgkmcnt(0)
	v_lshl_add_u64 v[68:69], s[26:27], 0, v[84:85]
	global_load_dword v76, v[68:69], off
	s_mov_b32 s5, 0x3cf5c28f
	s_waitcnt vmcnt(0)
	v_mul_f32_e32 v76, 0xbfb8aa3b, v76
	v_mfma_f32_32x32x16_bf16 v[18:33], v[88:91], v[70:73], v[18:33]
	v_lshl_add_u64 v[70:71], s[8:9], 0, v[84:85]
	v_lshl_add_u64 v[72:73], s[24:25], 0, v[84:85]
	global_load_dword v75, v[70:71], off
	global_load_dword v67, v[72:73], off
	v_exp_f32_e32 v79, v76
	v_mfma_f32_32x32x16_bf16 v[50:65], v[88:91], v[92:95], v[50:65]
	v_cmp_ngt_f32_e32 vcc, s5, v79
	v_mfma_f32_32x32x16_bf16 v[2:17], v[88:91], v[80:83], v[2:17]
	s_and_saveexec_b64 s[8:9], vcc
	s_xor_b64 s[10:11], exec, s[8:9]
	s_cbranch_execz .LBB0_563
	v_add_f32_e32 v76, 1.0, v79
	s_mov_b32 s5, 0x800000
	v_cmp_gt_f32_e32 vcc, s5, v76
	s_mov_b32 s5, 0x3f317217
	s_nop 0
	v_cndmask_b32_e64 v79, 0, 32, vcc
	v_ldexp_f32 v76, v76, v79
	v_log_f32_e32 v76, v76
	s_nop 0
	v_mul_f32_e32 v79, 0x3f317217, v76
	v_fma_f32 v79, v76, s5, -v79
	v_fmac_f32_e32 v79, 0x3377d1cf, v76
	s_mov_b32 s5, 0x7f800000
	v_fmac_f32_e32 v79, 0x3f317217, v76
	v_cmp_lt_f32_e64 s[8:9], |v76|, s5
	s_nop 1
	v_cndmask_b32_e64 v76, v76, v79, s[8:9]
	v_mov_b32_e32 v79, 0x41b17218
	v_cndmask_b32_e32 v79, 0, v79, vcc
	v_sub_f32_e32 v76, v76, v79

; DI float bf2f(u16 v) { return __uint_as_float(((unsigned)v) << 16); }
; DI int crow(int r, int hh) { return (r & 3) + 8 * (r >> 2) + 4 * hh; }
;     ...
;     if (pass == 3) {
; #pragma unroll
;       for (int r = 0; r < 16; ++r) {
;         const int t = th * 32 + crow(r, hh);
;         float hv = sb[cl * 65 + t];
;         hsum[r] = dir ? (hsum[r] + hv) : hv;
;       }
;     }
;     __syncthreads();
;   }
;   if (pass == 3) {
;     u16* Zlg = (u16*)(p->ws + OFF_ZLG);
; #pragma unroll
;     for (int r = 0; r < 16; ++r) {
;       const int t = th * 32 + crow(r, hh);
;       const size_t idx = (size_t)(base + t) * 512 + cg;
;       const u16 ov = f2bf(hsum[r] * gelu_tanh(bf2f(Zlg[idx])));
;       if (dummy) ((u16*)(p->ws + OFF_END))[(size_t)((base + t) & 2047) * 512 + cg] = ov; else Zlg[idx] = ov;
;     }
.LBB0_1154:
	s_or_b64 exec, exec, s[8:9]
	s_waitcnt lgkmcnt(0)
	s_barrier
	ds_read2_b32 v[2:3], v60 offset1:1
	v_lshlrev_b32_e32 v198, 1, v72
	v_lshl_add_u64 v[4:5], s[6:7], 0, v[198:199]
	s_mov_b64 s[2:3], 0x4950000
	v_lshl_add_u64 v[4:5], v[4:5], 0, s[2:3]
	s_waitcnt lgkmcnt(0)
	v_add_f32_e32 v17, v48, v2
	v_add_f32_e32 v20, v49, v3
	ds_read2_b32 v[2:3], v58 offset1:1
	s_waitcnt lgkmcnt(0)
	v_add_f32_e32 v21, v46, v2
	v_add_f32_e32 v22, v47, v3
	ds_read2_b32 v[2:3], v56 offset1:1
	s_waitcnt lgkmcnt(0)
	v_add_f32_e32 v23, v44, v2
	v_add_f32_e32 v16, v45, v3
	ds_read2_b32 v[2:3], v55 offset1:1
	s_waitcnt lgkmcnt(0)
	v_add_f32_e32 v15, v42, v2
	v_add_f32_e32 v14, v43, v3
	ds_read2_b32 v[2:3], v54 offset1:1
	s_waitcnt lgkmcnt(0)
	v_add_f32_e32 v13, v40, v2
	v_add_f32_e32 v12, v41, v3
	ds_read2_b32 v[2:3], v53 offset1:1
	s_waitcnt lgkmcnt(0)
	v_add_f32_e32 v11, v38, v2
	v_add_f32_e32 v10, v39, v3
	ds_read2_b32 v[2:3], v52 offset1:1
	s_waitcnt lgkmcnt(0)
	v_add_f32_e32 v9, v36, v2
	v_add_f32_e32 v8, v37, v3
	ds_read2_b32 v[2:3], v51 offset1:1
	s_waitcnt lgkmcnt(0)
	s_barrier
	v_add_f32_e32 v7, v34, v2
	v_add_u32_e32 v2, s27, v50
	v_add_f32_e32 v6, v35, v3
	s_add_u32 s2, s6, 0x4950000
	s_addc_u32 s3, s7, 0
	v_lshlrev_b32_e32 v96, 10, v2
	v_lshl_add_u32 v96, v72, 1, v96
	v_add_u32_e32 v97, 0x2000, v96
	v_add_u32_e32 v98, 0x4000, v96
	v_add_u32_e32 v99, 0x6000, v96
	global_load_ushort v80, v96, s[2:3]
	global_load_ushort v81, v96, s[2:3] offset:1024
	global_load_ushort v82, v96, s[2:3] offset:2048
	global_load_ushort v83, v96, s[2:3] offset:3072
	global_load_ushort v84, v97, s[2:3]
	global_load_ushort v85, v97, s[2:3] offset:1024
	global_load_ushort v86, v97, s[2:3] offset:2048
	global_load_ushort v87, v97, s[2:3] offset:3072
	global_load_ushort v88, v98, s[2:3]
	global_load_ushort v89, v98, s[2:3] offset:1024
	global_load_ushort v90, v98, s[2:3] offset:2048
	global_load_ushort v91, v98, s[2:3] offset:3072
	global_load_ushort v92, v99, s[2:3]
	global_load_ushort v93, v99, s[2:3] offset:1024
	global_load_ushort v94, v99, s[2:3] offset:2048
	global_load_ushort v95, v99, s[2:3] offset:3072
	s_waitcnt vmcnt(15)
	v_lshlrev_b32_e32 v80, 16, v80
	v_mul_f32_e32 v100, 0x3d372713, v80
	v_mul_f32_e32 v100, v100, v80
	v_fma_f32 v100, v100, v80, v80
	v_mul_f32_e32 v100, 0x3f4c422a, v100
	v_add_f32_e32 v100, v100, v100
	v_mul_f32_e32 v100, 0x3fb8aa3b, v100
	v_exp_f32_e32 v100, v100
	v_mul_f32_e32 v80, 0.5, v80
	v_add_f32_e32 v100, 1.0, v100
	v_rcp_f32_e32 v100, v100
	s_nop 0
	v_fma_f32 v100, v100, -2.0, 1.0
	v_add_f32_e32 v100, 1.0, v100
	v_mul_f32_e32 v80, v80, v100
	v_mul_f32_e32 v80, v17, v80
	v_cvt_pk_bf16_f32 v80, v80, v80
	global_store_short v96, v80, s[2:3]
	s_waitcnt vmcnt(15)
	v_lshlrev_b32_e32 v81, 16, v81
	v_mul_f32_e32 v100, 0x3d372713, v81
	v_mul_f32_e32 v100, v100, v81
	v_fma_f32 v100, v100, v81, v81
	v_mul_f32_e32 v100, 0x3f4c422a, v100
	v_add_f32_e32 v100, v100, v100
	v_mul_f32_e32 v100, 0x3fb8aa3b, v100
	v_exp_f32_e32 v100, v100
	v_mul_f32_e32 v81, 0.5, v81
	v_add_f32_e32 v100, 1.0, v100
	v_rcp_f32_e32 v100, v100
	s_nop 0
	v_fma_f32 v100, v100, -2.0, 1.0
	v_add_f32_e32 v100, 1.0, v100
	v_mul_f32_e32 v81, v81, v100
	v_mul_f32_e32 v81, v20, v81
	v_cvt_pk_bf16_f32 v81, v81, v81
	global_store_short v96, v81, s[2:3] offset:1024
	s_waitcnt vmcnt(15)
	v_lshlrev_b32_e32 v82, 16, v82
	v_mul_f32_e32 v100, 0x3d372713, v82
	v_mul_f32_e32 v100, v100, v82
	v_fma_f32 v100, v100, v82, v82
	v_mul_f32_e32 v100, 0x3f4c422a, v100
	v_add_f32_e32 v100, v100, v100
	v_mul_f32_e32 v100, 0x3fb8aa3b, v100
	v_exp_f32_e32 v100, v100
	v_mul_f32_e32 v82, 0.5, v82
	v_add_f32_e32 v100, 1.0, v100
	v_rcp_f32_e32 v100, v100
	s_nop 0
	v_fma_f32 v100, v100, -2.0, 1.0
	v_add_f32_e32 v100, 1.0, v100
	v_mul_f32_e32 v82, v82, v100
	v_mul_f32_e32 v82, v21, v82
	v_cvt_pk_bf16_f32 v82, v82, v82
	global_store_short v96, v82, s[2:3] offset:2048
	s_waitcnt vmcnt(15)
	v_lshlrev_b32_e32 v83, 16, v83
	v_mul_f32_e32 v100, 0x3d372713, v83
	v_mul_f32_e32 v100, v100, v83
	v_fma_f32 v100, v100, v83, v83
	v_mul_f32_e32 v100, 0x3f4c422a, v100
	v_add_f32_e32 v100, v100, v100
	v_mul_f32_e32 v100, 0x3fb8aa3b, v100
	v_exp_f32_e32 v100, v100
	v_mul_f32_e32 v83, 0.5, v83
	v_add_f32_e32 v100, 1.0, v100
	v_rcp_f32_e32 v100, v100
	s_nop 0
	v_fma_f32 v100, v100, -2.0, 1.0
	v_add_f32_e32 v100, 1.0, v100
	v_mul_f32_e32 v83, v83, v100
	v_mul_f32_e32 v83, v22, v83
	v_cvt_pk_bf16_f32 v83, v83, v83
	global_store_short v96, v83, s[2:3] offset:3072
	s_waitcnt vmcnt(15)
	v_lshlrev_b32_e32 v84, 16, v84
	v_mul_f32_e32 v100, 0x3d372713, v84
	v_mul_f32_e32 v100, v100, v84
	v_fma_f32 v100, v100, v84, v84
	v_mul_f32_e32 v100, 0x3f4c422a, v100
	v_add_f32_e32 v100, v100, v100
	v_mul_f32_e32 v100, 0x3fb8aa3b, v100
	v_exp_f32_e32 v100, v100
	v_mul_f32_e32 v84, 0.5, v84
	v_add_f32_e32 v100, 1.0, v100
	v_rcp_f32_e32 v100, v100
	s_nop 0
	v_fma_f32 v100, v100, -2.0, 1.0
	v_add_f32_e32 v100, 1.0, v100
	v_mul_f32_e32 v84, v84, v100
	v_mul_f32_e32 v84, v23, v84
	v_cvt_pk_bf16_f32 v84, v84, v84
	global_store_short v97, v84, s[2:3]
	s_waitcnt vmcnt(15)
	v_lshlrev_b32_e32 v85, 16, v85
	v_mul_f32_e32 v100, 0x3d372713, v85
	v_mul_f32_e32 v100, v100, v85
	v_fma_f32 v100, v100, v85, v85
	v_mul_f32_e32 v100, 0x3f4c422a, v100
	v_add_f32_e32 v100, v100, v100
	v_mul_f32_e32 v100, 0x3fb8aa3b, v100
	v_exp_f32_e32 v100, v100
	v_mul_f32_e32 v85, 0.5, v85
	v_add_f32_e32 v100, 1.0, v100
	v_rcp_f32_e32 v100, v100
	s_nop 0
	v_fma_f32 v100, v100, -2.0, 1.0
	v_add_f32_e32 v100, 1.0, v100
	v_mul_f32_e32 v85, v85, v100
	v_mul_f32_e32 v85, v16, v85
	v_cvt_pk_bf16_f32 v85, v85, v85
	global_store_short v97, v85, s[2:3] offset:1024
	s_waitcnt vmcnt(15)
; DI float bf2f(u16 v) { return __uint_as_float(((unsigned)v) << 16); }
; DI int crow(int r, int hh) { return (r & 3) + 8 * (r >> 2) + 4 * hh; }
;     ...
;   if (pass == 3) {
;     u16* Zlg = (u16*)(p->ws + OFF_ZLG);
; #pragma unroll
;     for (int r = 0; r < 16; ++r) {
;       const int t = th * 32 + crow(r, hh);
;       const size_t idx = (size_t)(base + t) * 512 + cg;
;       const u16 ov = f2bf(hsum[r] * gelu_tanh(bf2f(Zlg[idx])));
;       if (dummy) ((u16*)(p->ws + OFF_END))[(size_t)((base + t) & 2047) * 512 + cg] = ov; else Zlg[idx] = ov;
;     }
	v_lshlrev_b32_e32 v86, 16, v86
	v_mul_f32_e32 v100, 0x3d372713, v86
	v_mul_f32_e32 v100, v100, v86
	v_fma_f32 v100, v100, v86, v86
	v_mul_f32_e32 v100, 0x3f4c422a, v100
	v_add_f32_e32 v100, v100, v100
	v_mul_f32_e32 v100, 0x3fb8aa3b, v100
	v_exp_f32_e32 v100, v100
	v_mul_f32_e32 v86, 0.5, v86
	v_add_f32_e32 v100, 1.0, v100
	v_rcp_f32_e32 v100, v100
	s_nop 0
	v_fma_f32 v100, v100, -2.0, 1.0
	v_add_f32_e32 v100, 1.0, v100
	v_mul_f32_e32 v86, v86, v100
	v_mul_f32_e32 v86, v15, v86
	v_cvt_pk_bf16_f32 v86, v86, v86
	global_store_short v97, v86, s[2:3] offset:2048
	s_waitcnt vmcnt(15)
	v_lshlrev_b32_e32 v87, 16, v87
	v_mul_f32_e32 v100, 0x3d372713, v87
	v_mul_f32_e32 v100, v100, v87
	v_fma_f32 v100, v100, v87, v87
	v_mul_f32_e32 v100, 0x3f4c422a, v100
	v_add_f32_e32 v100, v100, v100
	v_mul_f32_e32 v100, 0x3fb8aa3b, v100
	v_exp_f32_e32 v100, v100
	v_mul_f32_e32 v87, 0.5, v87
	v_add_f32_e32 v100, 1.0, v100
	v_rcp_f32_e32 v100, v100
	s_nop 0
	v_fma_f32 v100, v100, -2.0, 1.0
	v_add_f32_e32 v100, 1.0, v100
	v_mul_f32_e32 v87, v87, v100
	v_mul_f32_e32 v87, v14, v87
	v_cvt_pk_bf16_f32 v87, v87, v87
	global_store_short v97, v87, s[2:3] offset:3072
	s_waitcnt vmcnt(15)
	v_lshlrev_b32_e32 v88, 16, v88
	v_mul_f32_e32 v100, 0x3d372713, v88
	v_mul_f32_e32 v100, v100, v88
	v_fma_f32 v100, v100, v88, v88
	v_mul_f32_e32 v100, 0x3f4c422a, v100
	v_add_f32_e32 v100, v100, v100
	v_mul_f32_e32 v100, 0x3fb8aa3b, v100
	v_exp_f32_e32 v100, v100
	v_mul_f32_e32 v88, 0.5, v88
	v_add_f32_e32 v100, 1.0, v100
	v_rcp_f32_e32 v100, v100
	s_nop 0
	v_fma_f32 v100, v100, -2.0, 1.0
	v_add_f32_e32 v100, 1.0, v100
	v_mul_f32_e32 v88, v88, v100
	v_mul_f32_e32 v88, v13, v88
	v_cvt_pk_bf16_f32 v88, v88, v88
	global_store_short v98, v88, s[2:3]
	s_waitcnt vmcnt(15)
	v_lshlrev_b32_e32 v89, 16, v89
	v_mul_f32_e32 v100, 0x3d372713, v89
	v_mul_f32_e32 v100, v100, v89
	v_fma_f32 v100, v100, v89, v89
	v_mul_f32_e32 v100, 0x3f4c422a, v100
	v_add_f32_e32 v100, v100, v100
	v_mul_f32_e32 v100, 0x3fb8aa3b, v100
	v_exp_f32_e32 v100, v100
	v_mul_f32_e32 v89, 0.5, v89
	v_add_f32_e32 v100, 1.0, v100
	v_rcp_f32_e32 v100, v100
	s_nop 0
	v_fma_f32 v100, v100, -2.0, 1.0
	v_add_f32_e32 v100, 1.0, v100
	v_mul_f32_e32 v89, v89, v100
	v_mul_f32_e32 v89, v12, v89
	v_cvt_pk_bf16_f32 v89, v89, v89
	global_store_short v98, v89, s[2:3] offset:1024
	s_waitcnt vmcnt(15)
	v_lshlrev_b32_e32 v90, 16, v90
	v_mul_f32_e32 v100, 0x3d372713, v90
	v_mul_f32_e32 v100, v100, v90
	v_fma_f32 v100, v100, v90, v90
	v_mul_f32_e32 v100, 0x3f4c422a, v100
	v_add_f32_e32 v100, v100, v100
	v_mul_f32_e32 v100, 0x3fb8aa3b, v100
	v_exp_f32_e32 v100, v100
	v_mul_f32_e32 v90, 0.5, v90
	v_add_f32_e32 v100, 1.0, v100
	v_rcp_f32_e32 v100, v100
	s_nop 0
	v_fma_f32 v100, v100, -2.0, 1.0
	v_add_f32_e32 v100, 1.0, v100
	v_mul_f32_e32 v90, v90, v100
	v_mul_f32_e32 v90, v11, v90
	v_cvt_pk_bf16_f32 v90, v90, v90
	global_store_short v98, v90, s[2:3] offset:2048
	s_waitcnt vmcnt(15)
	v_lshlrev_b32_e32 v91, 16, v91
	v_mul_f32_e32 v100, 0x3d372713, v91
	v_mul_f32_e32 v100, v100, v91
	v_fma_f32 v100, v100, v91, v91
	v_mul_f32_e32 v100, 0x3f4c422a, v100
	v_add_f32_e32 v100, v100, v100
	v_mul_f32_e32 v100, 0x3fb8aa3b, v100
	v_exp_f32_e32 v100, v100
	v_mul_f32_e32 v91, 0.5, v91
	v_add_f32_e32 v100, 1.0, v100
	v_rcp_f32_e32 v100, v100
	s_nop 0
	v_fma_f32 v100, v100, -2.0, 1.0
	v_add_f32_e32 v100, 1.0, v100
	v_mul_f32_e32 v91, v91, v100
	v_mul_f32_e32 v91, v10, v91
	v_cvt_pk_bf16_f32 v91, v91, v91
	global_store_short v98, v91, s[2:3] offset:3072
	s_waitcnt vmcnt(15)
	v_lshlrev_b32_e32 v92, 16, v92
	v_mul_f32_e32 v100, 0x3d372713, v92
	v_mul_f32_e32 v100, v100, v92
	v_fma_f32 v100, v100, v92, v92
	v_mul_f32_e32 v100, 0x3f4c422a, v100
	v_add_f32_e32 v100, v100, v100
	v_mul_f32_e32 v100, 0x3fb8aa3b, v100
	v_exp_f32_e32 v100, v100
	v_mul_f32_e32 v92, 0.5, v92
	v_add_f32_e32 v100, 1.0, v100
	v_rcp_f32_e32 v100, v100
	s_nop 0
	v_fma_f32 v100, v100, -2.0, 1.0
	v_add_f32_e32 v100, 1.0, v100
	v_mul_f32_e32 v92, v92, v100
	v_mul_f32_e32 v92, v9, v92
	v_cvt_pk_bf16_f32 v92, v92, v92
	global_store_short v99, v92, s[2:3]
	s_waitcnt vmcnt(15)
	v_lshlrev_b32_e32 v93, 16, v93
	v_mul_f32_e32 v100, 0x3d372713, v93
	v_mul_f32_e32 v100, v100, v93
	v_fma_f32 v100, v100, v93, v93
	v_mul_f32_e32 v100, 0x3f4c422a, v100
	v_add_f32_e32 v100, v100, v100
	v_mul_f32_e32 v100, 0x3fb8aa3b, v100
	v_exp_f32_e32 v100, v100
	v_mul_f32_e32 v93, 0.5, v93
	v_add_f32_e32 v100, 1.0, v100
	v_rcp_f32_e32 v100, v100
	s_nop 0
	v_fma_f32 v100, v100, -2.0, 1.0
	v_add_f32_e32 v100, 1.0, v100
	v_mul_f32_e32 v93, v93, v100
	v_mul_f32_e32 v93, v8, v93
	v_cvt_pk_bf16_f32 v93, v93, v93
	global_store_short v99, v93, s[2:3] offset:1024
	s_waitcnt vmcnt(15)
	v_lshlrev_b32_e32 v94, 16, v94
	v_mul_f32_e32 v100, 0x3d372713, v94
	v_mul_f32_e32 v100, v100, v94
	v_fma_f32 v100, v100, v94, v94
	v_mul_f32_e32 v100, 0x3f4c422a, v100
	v_add_f32_e32 v100, v100, v100
	v_mul_f32_e32 v100, 0x3fb8aa3b, v100
	v_exp_f32_e32 v100, v100
	v_mul_f32_e32 v94, 0.5, v94
	v_add_f32_e32 v100, 1.0, v100
	v_rcp_f32_e32 v100, v100
	s_nop 0
	v_fma_f32 v100, v100, -2.0, 1.0
	v_add_f32_e32 v100, 1.0, v100
	v_mul_f32_e32 v94, v94, v100
	v_mul_f32_e32 v94, v7, v94
	v_cvt_pk_bf16_f32 v94, v94, v94
	global_store_short v99, v94, s[2:3] offset:2048
	s_waitcnt vmcnt(15)
	v_lshlrev_b32_e32 v95, 16, v95
	v_mul_f32_e32 v100, 0x3d372713, v95
	v_mul_f32_e32 v100, v100, v95
	v_fma_f32 v100, v100, v95, v95
	v_mul_f32_e32 v100, 0x3f4c422a, v100
	v_add_f32_e32 v100, v100, v100
	v_mul_f32_e32 v100, 0x3fb8aa3b, v100
	v_exp_f32_e32 v100, v100
	v_mul_f32_e32 v95, 0.5, v95
	v_add_f32_e32 v100, 1.0, v100
	v_rcp_f32_e32 v100, v100
	s_nop 0
	v_fma_f32 v100, v100, -2.0, 1.0
	v_add_f32_e32 v100, 1.0, v100
	v_mul_f32_e32 v95, v95, v100
	v_mul_f32_e32 v95, v6, v95
	v_cvt_pk_bf16_f32 v95, v95, v95
	global_store_short v99, v95, s[2:3] offset:3072

; DI float bf2f(u16 v) { return __uint_as_float(((unsigned)v) << 16); }
;     ...
;     const int c = tid & 63, tq = tid >> 6, cg = g * 64 + c;
;     const float w0 = p->lru_conv_w[(l * 4 + 0) * 512 + cg], w1 = p->lru_conv_w[(l * 4 + 1) * 512 + cg];
;     const float w2 = p->lru_conv_w[(l * 4 + 2) * 512 + cg], w3 = p->lru_conv_w[(l * 4 + 3) * 512 + cg];
;     const float bias = p->lru_conv_b[l * 512 + cg];
;     auto ld = [&](int tt) -> float {
;       int tp = tpos0 + tt;
;       return (tp >= 0 && tp < seglen) ? bf2f(Zlx[(size_t)(base + tt) * 512 + cg]) : 0.f;
;     };
;     const int t0 = tq * 16;
;     float xv[19];
; #pragma unroll
;     for (int e = 0; e < 19; ++e) xv[e] = ld(t0 - 2 + e);
.LBB0_1168:
	s_load_dwordx2 s[6:7], s[16:17], 0x130
	s_waitcnt lgkmcnt(0)
	s_barrier
	s_load_dwordx4 s[8:11], s[16:17], 0x68
	s_and_b32 s29, s5, 7
	v_and_b32_e32 v77, 63, v76
	s_lshl_b32 s28, s29, 6
	v_or_b32_e32 v4, s28, v77
	s_waitcnt lgkmcnt(0)
	v_mov_b32_e32 v2, s8
	v_mov_b32_e32 v3, s9
	v_or_b32_e32 v198, s77, v4
	v_lshl_add_u64 v[2:3], v[198:199], 2, v[2:3]
	v_add_co_u32_e32 v12, vcc, s47, v2
	v_mov_b32_e32 v10, s10
	v_mov_b32_e32 v11, s11
	v_addc_co_u32_e32 v13, vcc, 0, v3, vcc
	global_load_dword v5, v[2:3], off
	global_load_dword v8, v[2:3], off offset:2048
	global_load_dword v7, v[12:13], off
	global_load_dword v6, v[12:13], off offset:2048
	v_or_b32_e32 v198, s80, v4
	v_lshl_add_u64 v[2:3], v[198:199], 2, v[10:11]
	global_load_dword v9, v[2:3], off
	v_ashrrev_i32_e32 v10, 6, v76
	v_lshlrev_b32_e32 v14, 4, v10
	v_lshlrev_b32_e32 v31, 1, v4
	v_add_u32_e32 v38, s27, v14
	s_add_u32 s8, s6, 0x3850000
	s_addc_u32 s9, s7, 0
	v_lshl_add_u32 v31, v38, 10, v31
	v_add_u32_e32 v34, 0x1000, v31
	v_add_u32_e32 v35, 0x2000, v31
	v_add_u32_e32 v36, 0x3000, v31
	v_add_u32_e32 v37, 0x4000, v31
	global_load_ushort v12, v31, s[8:9] offset:-2048
	global_load_ushort v11, v31, s[8:9] offset:-1024
	global_load_ushort v15, v31, s[8:9]
	global_load_ushort v13, v31, s[8:9] offset:1024
	global_load_ushort v18, v31, s[8:9] offset:2048
	global_load_ushort v16, v31, s[8:9] offset:3072
	global_load_ushort v20, v34, s[8:9]
	global_load_ushort v19, v34, s[8:9] offset:1024
	global_load_ushort v22, v34, s[8:9] offset:2048
	global_load_ushort v21, v34, s[8:9] offset:3072
	global_load_ushort v24, v35, s[8:9]
	global_load_ushort v23, v35, s[8:9] offset:1024
	global_load_ushort v26, v35, s[8:9] offset:2048
	global_load_ushort v25, v35, s[8:9] offset:3072
	global_load_ushort v28, v36, s[8:9]
	global_load_ushort v27, v36, s[8:9] offset:1024
	global_load_ushort v30, v36, s[8:9] offset:2048
	global_load_ushort v29, v36, s[8:9] offset:3072
	global_load_ushort v39, v37, s[8:9]
	v_or_b32_e32 v17, 1, v14
	v_add_u32_e32 v38, s3, v14
	v_add_u32_e32 v40, -2, v38
	s_waitcnt vmcnt(0)
	v_cmp_gt_u32_e32 vcc, s4, v40
	v_lshlrev_b32_e32 v12, 16, v12
	v_add_u32_e32 v41, -1, v38
	v_cndmask_b32_e32 v12, 0, v12, vcc
	v_cmp_gt_u32_e32 vcc, s4, v41
	v_lshlrev_b32_e32 v11, 16, v11
	v_add_u32_e32 v40, 0, v38
	v_cndmask_b32_e32 v11, 0, v11, vcc
	v_cmp_gt_u32_e32 vcc, s4, v40
	v_lshlrev_b32_e32 v15, 16, v15
	v_add_u32_e32 v41, 1, v38
	v_cndmask_b32_e32 v15, 0, v15, vcc
	v_cmp_gt_u32_e32 vcc, s4, v41
	v_lshlrev_b32_e32 v13, 16, v13
	v_add_u32_e32 v40, 2, v38
	v_cndmask_b32_e32 v13, 0, v13, vcc
	v_cmp_gt_u32_e32 vcc, s4, v40
	v_lshlrev_b32_e32 v18, 16, v18
	v_add_u32_e32 v41, 3, v38
	v_cndmask_b32_e32 v18, 0, v18, vcc
	v_cmp_gt_u32_e32 vcc, s4, v41
	v_lshlrev_b32_e32 v16, 16, v16
	v_add_u32_e32 v40, 4, v38
	v_cndmask_b32_e32 v16, 0, v16, vcc
	v_cmp_gt_u32_e32 vcc, s4, v40
	v_lshlrev_b32_e32 v20, 16, v20
	v_add_u32_e32 v41, 5, v38
	v_cndmask_b32_e32 v20, 0, v20, vcc
	v_cmp_gt_u32_e32 vcc, s4, v41
	v_lshlrev_b32_e32 v19, 16, v19
	v_add_u32_e32 v40, 6, v38
	v_cndmask_b32_e32 v19, 0, v19, vcc
	v_cmp_gt_u32_e32 vcc, s4, v40
	v_lshlrev_b32_e32 v22, 16, v22
	v_add_u32_e32 v41, 7, v38
	v_cndmask_b32_e32 v22, 0, v22, vcc
	v_cmp_gt_u32_e32 vcc, s4, v41
	v_lshlrev_b32_e32 v21, 16, v21
	v_add_u32_e32 v40, 8, v38
	v_cndmask_b32_e32 v21, 0, v21, vcc
	v_cmp_gt_u32_e32 vcc, s4, v40
	v_lshlrev_b32_e32 v24, 16, v24
	v_add_u32_e32 v41, 9, v38
	v_cndmask_b32_e32 v24, 0, v24, vcc
	v_cmp_gt_u32_e32 vcc, s4, v41
	v_lshlrev_b32_e32 v23, 16, v23
	v_add_u32_e32 v40, 10, v38
	v_cndmask_b32_e32 v23, 0, v23, vcc
	v_cmp_gt_u32_e32 vcc, s4, v40
	v_lshlrev_b32_e32 v26, 16, v26
	v_add_u32_e32 v41, 11, v38
	v_cndmask_b32_e32 v26, 0, v26, vcc
	v_cmp_gt_u32_e32 vcc, s4, v41
	v_lshlrev_b32_e32 v25, 16, v25
	v_add_u32_e32 v40, 12, v38
	v_cndmask_b32_e32 v25, 0, v25, vcc
	v_cmp_gt_u32_e32 vcc, s4, v40
	v_lshlrev_b32_e32 v28, 16, v28
	v_add_u32_e32 v41, 13, v38
	v_cndmask_b32_e32 v28, 0, v28, vcc
	v_cmp_gt_u32_e32 vcc, s4, v41
	v_lshlrev_b32_e32 v27, 16, v27
	v_add_u32_e32 v40, 14, v38
	v_cndmask_b32_e32 v27, 0, v27, vcc
	v_cmp_gt_u32_e32 vcc, s4, v40
	v_lshlrev_b32_e32 v30, 16, v30
	v_add_u32_e32 v41, 15, v38
	v_cndmask_b32_e32 v30, 0, v30, vcc
	v_cmp_gt_u32_e32 vcc, s4, v41
	v_lshlrev_b32_e32 v29, 16, v29
	v_add_u32_e32 v40, 16, v38
	v_cndmask_b32_e32 v29, 0, v29, vcc
	v_cmp_gt_u32_e32 vcc, s4, v40
	v_lshlrev_b32_e32 v39, 16, v39
	s_nop 0
	v_cndmask_b32_e32 v39, 0, v39, vcc
	v_mov_b32_e32 v14, v39
	v_lshlrev_b32_e32 v2, 2, v77
	v_lshlrev_b32_e32 v3, 1, v77
	v_sub_u32_e32 v32, v2, v3
	s_waitcnt vmcnt(3)
;     ...
; #pragma unroll
;     for (int tt = 0; tt < 16; ++tt) {
;       const float y = w0 * xv[tt] + w1 * xv[tt + 1] + w2 * xv[tt + 2] + w3 * xv[tt + 3] + bias;
;       uf[(t0 + tt) * 65 + c] = y;
;       Au[(t0 + tt) * 72 + c] = f2bf(y);
;     }
;   }
;   if (pass == 3) {
;     const int part = tid >> 7, dir = (tid >> 6) & 1, c = tid & 63, cg = g * 64 + c;
;     const f32x2* ag = agg + ((size_t)(b * 68) * 2 + dir) * 512 + cg;
;     f32x2 ab[34];
; #pragma unroll
;     for (int e = 0; e < 34; ++e) {
;       const int sl = part * 34 + e;
;       int ch; bool valid;
;       if (dir == 0) { ch = sl; valid = sl < j; }
;       else { ch = (sl < 4) ? (3 - sl) : (71 - sl); valid = (j < 4) ? (sl < 4 && ch > j) : (sl < 4 || ch > j); }
;       ab[e] = valid ? ag[(size_t)ch * 1024] : mkf2(1.f, 0.f);
	v_mul_f32_e32 v3, v8, v11
	v_fmac_f32_e32 v3, v5, v12
	s_waitcnt vmcnt(2)
	v_fmac_f32_e32 v3, v7, v15
	s_waitcnt vmcnt(1)
	v_fmac_f32_e32 v3, v6, v13
	s_waitcnt vmcnt(0)
	v_add_f32_e32 v3, v9, v3
	s_movk_i32 s3, 0x1040
	v_mad_u64_u32 v[34:35], s[4:5], v10, s3, v[2:3]
	s_movk_i32 s3, 0x900
	ds_write_b32 v34, v3 offset:9216
	v_cvt_pk_bf16_f32 v3, v3, s0
	v_mad_u64_u32 v[34:35], s[4:5], v10, s3, v[32:33]
	ds_write_b16 v34, v3
	v_mul_f32_e32 v3, v8, v15
	v_fmac_f32_e32 v3, v5, v11
	v_fmac_f32_e32 v3, v7, v13
	v_fmac_f32_e32 v3, v6, v18
	v_add_f32_e32 v12, v9, v3
	v_mad_u64_u32 v[2:3], s[4:5], v17, s54, v[2:3]
	v_cvt_pk_bf16_f32 v3, v12, s0
	v_mad_u64_u32 v[10:11], s[4:5], v17, s60, v[32:33]
	ds_write_b16 v10, v3
	v_mul_f32_e32 v3, v8, v13
	v_fmac_f32_e32 v3, v5, v15
	v_fmac_f32_e32 v3, v7, v18
	v_fmac_f32_e32 v3, v6, v16
	v_add_f32_e32 v3, v9, v3
	v_add_u32_e32 v11, 0x2400, v2
	ds_write2_b32 v11, v12, v3 offset1:65
	v_cvt_pk_bf16_f32 v3, v3, s0
	ds_write_b16 v10, v3 offset:144
	v_mul_f32_e32 v3, v8, v18
	v_fmac_f32_e32 v3, v5, v13
	v_fmac_f32_e32 v3, v7, v16
	v_fmac_f32_e32 v3, v6, v20
	v_add_f32_e32 v3, v9, v3
	v_cvt_pk_bf16_f32 v12, v3, s0
	ds_write_b16 v10, v12 offset:288
	v_mul_f32_e32 v12, v8, v16
	v_fmac_f32_e32 v12, v5, v18
	v_fmac_f32_e32 v12, v7, v20
	v_fmac_f32_e32 v12, v6, v19
	v_add_f32_e32 v12, v9, v12
	ds_write2_b32 v11, v3, v12 offset0:130 offset1:195
	v_cvt_pk_bf16_f32 v3, v12, s0
	ds_write_b16 v10, v3 offset:432
	v_mul_f32_e32 v3, v8, v20
	v_fmac_f32_e32 v3, v5, v16
	v_fmac_f32_e32 v3, v7, v19
	v_fmac_f32_e32 v3, v6, v22
	v_add_f32_e32 v3, v9, v3
	v_cvt_pk_bf16_f32 v11, v3, s0
	ds_write_b16 v10, v11 offset:576
	v_mul_f32_e32 v11, v8, v19
	v_fmac_f32_e32 v11, v5, v20
	v_fmac_f32_e32 v11, v7, v22
	v_fmac_f32_e32 v11, v6, v21
	v_add_f32_e32 v11, v9, v11
	v_add_u32_e32 v12, 0x2800, v2
	ds_write2_b32 v12, v3, v11 offset0:4 offset1:69
	v_cvt_pk_bf16_f32 v3, v11, s0
	ds_write_b16 v10, v3 offset:720
	v_mul_f32_e32 v3, v8, v22
	v_fmac_f32_e32 v3, v5, v19
	v_fmac_f32_e32 v3, v7, v21
	v_fmac_f32_e32 v3, v6, v24
	v_add_f32_e32 v3, v9, v3
	v_cvt_pk_bf16_f32 v11, v3, s0
	ds_write_b16 v10, v11 offset:864
	v_mul_f32_e32 v11, v8, v21
	v_fmac_f32_e32 v11, v5, v22
	v_fmac_f32_e32 v11, v7, v24
	v_fmac_f32_e32 v11, v6, v23
	v_add_f32_e32 v11, v9, v11
	ds_write2_b32 v12, v3, v11 offset0:134 offset1:199
	v_cvt_pk_bf16_f32 v3, v11, s0
	ds_write_b16 v10, v3 offset:1008
	v_mul_f32_e32 v3, v8, v24
	v_fmac_f32_e32 v3, v5, v21
	v_fmac_f32_e32 v3, v7, v23
	v_fmac_f32_e32 v3, v6, v26
	v_add_f32_e32 v3, v9, v3
	v_cvt_pk_bf16_f32 v11, v3, s0
	ds_write_b16 v10, v11 offset:1152
	v_mul_f32_e32 v11, v8, v23
	v_fmac_f32_e32 v11, v5, v24
	v_fmac_f32_e32 v11, v7, v26
	v_fmac_f32_e32 v11, v6, v25
	v_add_f32_e32 v11, v9, v11
	v_add_u32_e32 v12, 0x2c00, v2
	ds_write2_b32 v12, v3, v11 offset0:8 offset1:73
	v_cvt_pk_bf16_f32 v3, v11, s0
	ds_write_b16 v10, v3 offset:1296
	v_mul_f32_e32 v3, v8, v26
	v_fmac_f32_e32 v3, v5, v23
	v_fmac_f32_e32 v3, v7, v25
	v_fmac_f32_e32 v3, v6, v28
	v_add_f32_e32 v3, v9, v3
	v_cvt_pk_bf16_f32 v11, v3, s0
	ds_write_b16 v10, v11 offset:1440
	v_mul_f32_e32 v11, v8, v25
	v_fmac_f32_e32 v11, v5, v26
	v_fmac_f32_e32 v11, v7, v28
	v_fmac_f32_e32 v11, v6, v27
	v_add_f32_e32 v11, v9, v11
	ds_write2_b32 v12, v3, v11 offset0:138 offset1:203
	v_cvt_pk_bf16_f32 v3, v11, s0
	ds_write_b16 v10, v3 offset:1584
	v_mul_f32_e32 v3, v8, v28
	v_fmac_f32_e32 v3, v5, v25
	v_fmac_f32_e32 v3, v7, v27
	v_fmac_f32_e32 v3, v6, v30
	v_add_f32_e32 v3, v9, v3
	v_cvt_pk_bf16_f32 v11, v3, s0
	ds_write_b16 v10, v11 offset:1728
	v_mul_f32_e32 v11, v8, v27
	v_fmac_f32_e32 v11, v5, v28
	v_fmac_f32_e32 v11, v7, v30
	v_fmac_f32_e32 v11, v6, v29
	v_add_f32_e32 v11, v9, v11
	v_add_u32_e32 v12, 0x3000, v2
	ds_write2_b32 v12, v3, v11 offset0:12 offset1:77
	v_cvt_pk_bf16_f32 v3, v11, s0
	ds_write_b16 v10, v3 offset:1872
	v_mul_f32_e32 v3, v8, v30
	v_fmac_f32_e32 v3, v5, v27
	v_fmac_f32_e32 v3, v7, v29
	v_fmac_f32_e32 v3, v6, v14
	v_add_f32_e32 v3, v9, v3
	ds_write_b32 v2, v3 offset:12856
	v_cvt_pk_bf16_f32 v2, v3, s0
	ds_write_b16 v10, v2 offset:2016
	v_ashrrev_i32_e32 v78, 7, v76
	v_and_b32_e32 v2, 64, v76
	v_mul_lo_u32 v74, v78, 34
	v_cmp_ne_u32_e64 s[8:9], 0, v2
	s_and_saveexec_b64 s[4:5], s[8:9]
	s_xor_b64 s[22:23], exec, s[4:5]
	s_cbranch_execz .LBB0_1211
	v_cmp_gt_i32_e64 s[10:11], 1, v78
	s_mov_b64 s[24:25], -1
	s_and_b64 vcc, exec, s[14:15]
	v_cndmask_b32_e64 v2, v242, 3, s[10:11]
	v_sub_u32_e32 v6, v2, v74
	v_cmp_lt_i32_e64 s[12:13], s34, v6
	s_cbranch_vccz .LBB0_1209
	s_or_b64 s[18:19], s[10:11], s[12:13]
	s_mov_b64 s[24:25], 0

; #define MFMA32(a, b, c) __builtin_amdgcn_mfma_f32_32x32x16_bf16((a), (b), (c), 0, 0, 0)
; DI void gemm_wide(f32x16 (&acc)[2][4], const u16* __restrict__ A, int lda, const u16* __restrict__ Bt, int ldb, int K,
;                   char* smem) {
;     ...
;   for (int k0 = 0; k0 < K; k0 += 64) {
;     __syncthreads();
; #pragma unroll
;     for (int i = 0; i < 4; ++i) *(u32x4*)(As + (lr + 32 * i) * LS + lk) = ra[i];
; #pragma unroll
;     for (int i = 0; i < 8; ++i) *(u32x4*)(Bs + (lr + 32 * i) * LS + lk) = rb[i];
;     __syncthreads();
;     if (k0 + 64 < K) {
;       const int k1 = k0 + 64 + lk;
; #pragma unroll
;       for (int i = 0; i < 4; ++i) ra[i] = *(const u32x4*)(A + (size_t)(lr + 32 * i) * lda + k1);
; #pragma unroll
;       for (int i = 0; i < 8; ++i) rb[i] = *(const u32x4*)(Bt + (size_t)(lr + 32 * i) * ldb + k1);
;     }
; #pragma unroll
;     for (int s = 0; s < 4; ++s) {
;       bf16x8 a[2], b[4];
; #pragma unroll
;       for (int i = 0; i < 2; ++i) a[i] = *(const bf16x8*)(As + (wm * 64 + i * 32 + l31) * LS + s * 16 + hh * 8);
; #pragma unroll
;       for (int j = 0; j < 4; ++j) b[j] = *(const bf16x8*)(Bs + (wn * 128 + j * 32 + l31) * LS + s * 16 + hh * 8);
; #pragma unroll
;       for (int i = 0; i < 2; ++i)
; #pragma unroll
;         for (int j = 0; j < 4; ++j) acc[i][j] = MFMA32(a[i], b[j], acc[i][j]);
;     }
;   }
.LBB0_1798:
	s_add_i32 s3, s3, 64
	v_lshl_add_u64 v[178:179], v[178:179], 0, s[50:51]
	v_lshl_add_u64 v[180:181], v[180:181], 0, s[50:51]
	s_andn2_b64 vcc, exec, s[22:23]
	ds_read_b128 v[236:239], v185 offset:32
	ds_read_b128 v[224:227], v186 offset:18464
	ds_read_b128 v[248:251], v185 offset:4640
	ds_read_b128 v[230:233], v186 offset:23072
	s_waitcnt lgkmcnt(8)
	v_mfma_f32_32x32x16_bf16 v[114:129], v[188:191], v[192:195], v[114:129]
	s_waitcnt lgkmcnt(7)
	v_mfma_f32_32x32x16_bf16 v[50:65], v[244:247], v[192:195], v[50:65]
	ds_read_b128 v[192:195], v186 offset:27680
	s_waitcnt lgkmcnt(7)
	v_mfma_f32_32x32x16_bf16 v[98:113], v[188:191], v[200:203], v[98:113]
	v_mfma_f32_32x32x16_bf16 v[34:49], v[244:247], v[200:203], v[34:49]
	ds_read_b128 v[200:203], v186 offset:32288
	s_waitcnt lgkmcnt(7)
	v_mfma_f32_32x32x16_bf16 v[82:97], v[188:191], v[204:207], v[82:97]
	v_mfma_f32_32x32x16_bf16 v[18:33], v[244:247], v[204:207], v[18:33]
	s_waitcnt lgkmcnt(6)
	v_mfma_f32_32x32x16_bf16 v[66:81], v[188:191], v[208:211], v[66:81]
	v_mfma_f32_32x32x16_bf16 v[2:17], v[244:247], v[208:211], v[2:17]
	ds_read_b128 v[188:191], v185 offset:64
	ds_read_b128 v[204:207], v186 offset:18496
	ds_read_b128 v[244:247], v185 offset:4672
	ds_read_b128 v[208:211], v186 offset:23104
	s_waitcnt lgkmcnt(8)
	v_mfma_f32_32x32x16_bf16 v[114:129], v[236:239], v[224:227], v[114:129]
	s_waitcnt lgkmcnt(7)
	v_mfma_f32_32x32x16_bf16 v[50:65], v[248:251], v[224:227], v[50:65]
	ds_read_b128 v[224:227], v186 offset:27712
	s_waitcnt lgkmcnt(7)
	v_mfma_f32_32x32x16_bf16 v[98:113], v[236:239], v[230:233], v[98:113]
	v_mfma_f32_32x32x16_bf16 v[34:49], v[248:251], v[230:233], v[34:49]
	ds_read_b128 v[230:233], v186 offset:32320
	s_waitcnt lgkmcnt(7)
	v_mfma_f32_32x32x16_bf16 v[82:97], v[236:239], v[192:195], v[82:97]
	v_mfma_f32_32x32x16_bf16 v[18:33], v[248:251], v[192:195], v[18:33]
	s_waitcnt lgkmcnt(6)
	v_mfma_f32_32x32x16_bf16 v[66:81], v[236:239], v[200:203], v[66:81]
	v_mfma_f32_32x32x16_bf16 v[2:17], v[248:251], v[200:203], v[2:17]
	ds_read_b128 v[236:239], v185 offset:96
	ds_read_b128 v[192:195], v186 offset:18528
	ds_read_b128 v[248:251], v185 offset:4704
	ds_read_b128 v[200:203], v186 offset:23136
	s_waitcnt lgkmcnt(8)
	v_mfma_f32_32x32x16_bf16 v[114:129], v[188:191], v[204:207], v[114:129]
	s_waitcnt lgkmcnt(7)
	v_mfma_f32_32x32x16_bf16 v[50:65], v[244:247], v[204:207], v[50:65]
	ds_read_b128 v[204:207], v186 offset:27744
	s_waitcnt lgkmcnt(7)
	v_mfma_f32_32x32x16_bf16 v[98:113], v[188:191], v[208:211], v[98:113]
	v_mfma_f32_32x32x16_bf16 v[34:49], v[244:247], v[208:211], v[34:49]
	ds_read_b128 v[208:211], v186 offset:32352
	s_waitcnt lgkmcnt(7)
	v_mfma_f32_32x32x16_bf16 v[82:97], v[188:191], v[224:227], v[82:97]
	v_mfma_f32_32x32x16_bf16 v[18:33], v[244:247], v[224:227], v[18:33]
	s_waitcnt lgkmcnt(6)
	v_mfma_f32_32x32x16_bf16 v[66:81], v[188:191], v[230:233], v[66:81]
	v_mfma_f32_32x32x16_bf16 v[2:17], v[244:247], v[230:233], v[2:17]
	s_waitcnt lgkmcnt(4)
	v_mfma_f32_32x32x16_bf16 v[114:129], v[236:239], v[192:195], v[114:129]
	s_waitcnt lgkmcnt(3)
	v_mfma_f32_32x32x16_bf16 v[50:65], v[248:251], v[192:195], v[50:65]
	s_waitcnt lgkmcnt(2)
	v_mfma_f32_32x32x16_bf16 v[98:113], v[236:239], v[200:203], v[98:113]
	v_mfma_f32_32x32x16_bf16 v[34:49], v[248:251], v[200:203], v[34:49]
	s_waitcnt lgkmcnt(1)
	v_mfma_f32_32x32x16_bf16 v[82:97], v[236:239], v[204:207], v[82:97]
	v_mfma_f32_32x32x16_bf16 v[18:33], v[248:251], v[204:207], v[18:33]
	s_waitcnt lgkmcnt(0)
	v_mfma_f32_32x32x16_bf16 v[66:81], v[236:239], v[208:211], v[66:81]
	v_mfma_f32_32x32x16_bf16 v[2:17], v[248:251], v[208:211], v[2:17]
	s_cbranch_vccz .LBB0_1784
.LBB0_1799:
	s_cmpk_gt_u32 s3, 0x3bf
	s_cselect_b64 s[22:23], -1, 0
	s_and_b64 vcc, exec, s[22:23]
	s_waitcnt lgkmcnt(0)
	s_barrier
	s_waitcnt vmcnt(11)
	ds_write_b128 v184, v[130:133]
	s_waitcnt vmcnt(10)
	ds_write_b128 v184, v[134:137] offset:4608
	s_waitcnt vmcnt(9)
	ds_write_b128 v184, v[138:141] offset:9216
	s_waitcnt vmcnt(8)
	ds_write_b128 v184, v[142:145] offset:13824
	s_waitcnt vmcnt(7)
	ds_write_b128 v184, v[146:149] offset:18432
	s_waitcnt vmcnt(6)
	ds_write_b128 v184, v[150:153] offset:23040
	s_waitcnt vmcnt(5)
	ds_write_b128 v184, v[154:157] offset:27648
	s_waitcnt vmcnt(4)
	ds_write_b128 v184, v[158:161] offset:32256
	s_waitcnt vmcnt(3)
	ds_write_b128 v184, v[162:165] offset:36864
	s_waitcnt vmcnt(2)
	ds_write_b128 v184, v[166:169] offset:41472
	s_waitcnt vmcnt(1)
	ds_write_b128 v184, v[170:173] offset:46080
	s_waitcnt vmcnt(0)
	ds_write_b128 v184, v[174:177] offset:50688
	s_waitcnt lgkmcnt(0)
	s_barrier
	ds_read_b128 v[188:191], v185
	ds_read_b128 v[192:195], v186 offset:18432
	ds_read_b128 v[244:247], v185 offset:4608
	ds_read_b128 v[200:203], v186 offset:23040
	ds_read_b128 v[204:207], v186 offset:27648
	ds_read_b128 v[208:211], v186 offset:32256
	s_cbranch_vccnz .LBB0_1798
	v_lshl_add_u64 v[138:139], v[180:181], 0, v[198:199]
	v_add_co_u32_e32 v130, vcc, 0xa6d0000, v138
	v_lshl_add_u64 v[170:171], v[178:179], 0, v[198:199]
	s_nop 0
	v_addc_co_u32_e32 v131, vcc, 0, v139, vcc
	v_add_co_u32_e32 v134, vcc, 0xa6e0000, v138
	s_mov_b32 s4, 0xe1e0000
	s_nop 0
	v_addc_co_u32_e32 v135, vcc, 0, v139, vcc
	v_add_co_u32_e32 v140, vcc, 0xa6f0000, v138
	global_load_dwordx4 v[130:133], v[130:131], off offset:128
	s_nop 0
	global_load_dwordx4 v[134:137], v[134:135], off offset:128
	v_addc_co_u32_e32 v141, vcc, 0, v139, vcc
	v_add_co_u32_e32 v142, vcc, 0xa700000, v138
	s_nop 1
	v_addc_co_u32_e32 v143, vcc, 0, v139, vcc
	v_add_co_u32_e32 v146, vcc, s4, v170
	global_load_dwordx4 v[138:141], v[140:141], off offset:128
	s_nop 0
	global_load_dwordx4 v[142:145], v[142:143], off offset:128
	v_addc_co_u32_e32 v147, vcc, 0, v171, vcc
	v_add_co_u32_e32 v150, vcc, 0xe1f0000, v170
	s_nop 1
	v_addc_co_u32_e32 v151, vcc, 0, v171, vcc
	v_add_co_u32_e32 v154, vcc, 0xe200000, v170
	global_load_dwordx4 v[146:149], v[146:147], off offset:128
	s_nop 0
	global_load_dwordx4 v[150:153], v[150:151], off offset:128
	v_addc_co_u32_e32 v155, vcc, 0, v171, vcc
	v_add_co_u32_e32 v158, vcc, 0xe210000, v170
	s_nop 1
	v_addc_co_u32_e32 v159, vcc, 0, v171, vcc
	v_add_co_u32_e32 v162, vcc, 0xe220000, v170
	global_load_dwordx4 v[154:157], v[154:155], off offset:128
	s_nop 0
	global_load_dwordx4 v[158:161], v[158:159], off offset:128
	v_addc_co_u32_e32 v163, vcc, 0, v171, vcc
	v_add_co_u32_e32 v166, vcc, 0xe230000, v170
	s_nop 1
	v_addc_co_u32_e32 v167, vcc, 0, v171, vcc
	v_add_co_u32_e32 v172, vcc, 0xe240000, v170
	global_load_dwordx4 v[162:165], v[162:163], off offset:128
	s_nop 0
	global_load_dwordx4 v[166:169], v[166:167], off offset:128
	v_addc_co_u32_e32 v173, vcc, 0, v171, vcc
	v_add_co_u32_e32 v174, vcc, 0xe250000, v170
	s_nop 1
	v_addc_co_u32_e32 v175, vcc, 0, v171, vcc
	global_load_dwordx4 v[170:173], v[172:173], off offset:128
	s_nop 0
	global_load_dwordx4 v[174:177], v[174:175], off offset:128
	s_branch .LBB0_1798

; #define MFMA32(a, b, c) __builtin_amdgcn_mfma_f32_32x32x16_bf16((a), (b), (c), 0, 0, 0)
; DI void gemm_wide(f32x16 (&acc)[2][4], const u16* __restrict__ A, int lda, const u16* __restrict__ Bt, int ldb, int K,
;                   char* smem) {
;     ...
;   for (int k0 = 0; k0 < K; k0 += 64) {
;     __syncthreads();
; #pragma unroll
;     for (int i = 0; i < 4; ++i) *(u32x4*)(As + (lr + 32 * i) * LS + lk) = ra[i];
; #pragma unroll
;     for (int i = 0; i < 8; ++i) *(u32x4*)(Bs + (lr + 32 * i) * LS + lk) = rb[i];
;     __syncthreads();
;     if (k0 + 64 < K) {
;       const int k1 = k0 + 64 + lk;
; #pragma unroll
;       for (int i = 0; i < 4; ++i) ra[i] = *(const u32x4*)(A + (size_t)(lr + 32 * i) * lda + k1);
; #pragma unroll
;       for (int i = 0; i < 8; ++i) rb[i] = *(const u32x4*)(Bt + (size_t)(lr + 32 * i) * ldb + k1);
;     }
; #pragma unroll
;     for (int s = 0; s < 4; ++s) {
;       bf16x8 a[2], b[4];
; #pragma unroll
;       for (int i = 0; i < 2; ++i) a[i] = *(const bf16x8*)(As + (wm * 64 + i * 32 + l31) * LS + s * 16 + hh * 8);
; #pragma unroll
;       for (int j = 0; j < 4; ++j) b[j] = *(const bf16x8*)(Bs + (wn * 128 + j * 32 + l31) * LS + s * 16 + hh * 8);
; #pragma unroll
;       for (int i = 0; i < 2; ++i)
; #pragma unroll
;         for (int j = 0; j < 4; ++j) acc[i][j] = MFMA32(a[i], b[j], acc[i][j]);
;     }
;   }
.LBB0_1934:
	s_add_i32 s4, s4, 64
	v_lshl_add_u64 v[178:179], v[178:179], 0, s[50:51]
	v_lshl_add_u64 v[180:181], v[180:181], 0, s[50:51]
	s_andn2_b64 vcc, exec, s[16:17]
	ds_read_b128 v[236:239], v185 offset:32
	ds_read_b128 v[224:227], v186 offset:18464
	ds_read_b128 v[248:251], v185 offset:4640
	ds_read_b128 v[230:233], v186 offset:23072
	s_waitcnt lgkmcnt(8)
	v_mfma_f32_32x32x16_bf16 v[114:129], v[188:191], v[192:195], v[114:129]
	s_waitcnt lgkmcnt(7)
	v_mfma_f32_32x32x16_bf16 v[50:65], v[244:247], v[192:195], v[50:65]
	ds_read_b128 v[192:195], v186 offset:27680
	s_waitcnt lgkmcnt(7)
	v_mfma_f32_32x32x16_bf16 v[98:113], v[188:191], v[200:203], v[98:113]
	v_mfma_f32_32x32x16_bf16 v[34:49], v[244:247], v[200:203], v[34:49]
	ds_read_b128 v[200:203], v186 offset:32288
	s_waitcnt lgkmcnt(7)
	v_mfma_f32_32x32x16_bf16 v[82:97], v[188:191], v[204:207], v[82:97]
	v_mfma_f32_32x32x16_bf16 v[18:33], v[244:247], v[204:207], v[18:33]
	s_waitcnt lgkmcnt(6)
	v_mfma_f32_32x32x16_bf16 v[66:81], v[188:191], v[208:211], v[66:81]
	v_mfma_f32_32x32x16_bf16 v[2:17], v[244:247], v[208:211], v[2:17]
	ds_read_b128 v[188:191], v185 offset:64
	ds_read_b128 v[204:207], v186 offset:18496
	ds_read_b128 v[244:247], v185 offset:4672
	ds_read_b128 v[208:211], v186 offset:23104
	s_waitcnt lgkmcnt(8)
	v_mfma_f32_32x32x16_bf16 v[114:129], v[236:239], v[224:227], v[114:129]
	s_waitcnt lgkmcnt(7)
	v_mfma_f32_32x32x16_bf16 v[50:65], v[248:251], v[224:227], v[50:65]
	ds_read_b128 v[224:227], v186 offset:27712
	s_waitcnt lgkmcnt(7)
	v_mfma_f32_32x32x16_bf16 v[98:113], v[236:239], v[230:233], v[98:113]
	v_mfma_f32_32x32x16_bf16 v[34:49], v[248:251], v[230:233], v[34:49]
	ds_read_b128 v[230:233], v186 offset:32320
	s_waitcnt lgkmcnt(7)
	v_mfma_f32_32x32x16_bf16 v[82:97], v[236:239], v[192:195], v[82:97]
	v_mfma_f32_32x32x16_bf16 v[18:33], v[248:251], v[192:195], v[18:33]
	s_waitcnt lgkmcnt(6)
	v_mfma_f32_32x32x16_bf16 v[66:81], v[236:239], v[200:203], v[66:81]
	v_mfma_f32_32x32x16_bf16 v[2:17], v[248:251], v[200:203], v[2:17]
	ds_read_b128 v[236:239], v185 offset:96
	ds_read_b128 v[192:195], v186 offset:18528
	ds_read_b128 v[248:251], v185 offset:4704
	ds_read_b128 v[200:203], v186 offset:23136
	s_waitcnt lgkmcnt(8)
	v_mfma_f32_32x32x16_bf16 v[114:129], v[188:191], v[204:207], v[114:129]
	s_waitcnt lgkmcnt(7)
	v_mfma_f32_32x32x16_bf16 v[50:65], v[244:247], v[204:207], v[50:65]
	ds_read_b128 v[204:207], v186 offset:27744
	s_waitcnt lgkmcnt(7)
	v_mfma_f32_32x32x16_bf16 v[98:113], v[188:191], v[208:211], v[98:113]
	v_mfma_f32_32x32x16_bf16 v[34:49], v[244:247], v[208:211], v[34:49]
	ds_read_b128 v[208:211], v186 offset:32352
	s_waitcnt lgkmcnt(7)
	v_mfma_f32_32x32x16_bf16 v[82:97], v[188:191], v[224:227], v[82:97]
	v_mfma_f32_32x32x16_bf16 v[18:33], v[244:247], v[224:227], v[18:33]
	s_waitcnt lgkmcnt(6)
	v_mfma_f32_32x32x16_bf16 v[66:81], v[188:191], v[230:233], v[66:81]
	v_mfma_f32_32x32x16_bf16 v[2:17], v[244:247], v[230:233], v[2:17]
	s_waitcnt lgkmcnt(4)
	v_mfma_f32_32x32x16_bf16 v[114:129], v[236:239], v[192:195], v[114:129]
	s_waitcnt lgkmcnt(3)
	v_mfma_f32_32x32x16_bf16 v[50:65], v[248:251], v[192:195], v[50:65]
	s_waitcnt lgkmcnt(2)
	v_mfma_f32_32x32x16_bf16 v[98:113], v[236:239], v[200:203], v[98:113]
	v_mfma_f32_32x32x16_bf16 v[34:49], v[248:251], v[200:203], v[34:49]
	s_waitcnt lgkmcnt(1)
	v_mfma_f32_32x32x16_bf16 v[82:97], v[236:239], v[204:207], v[82:97]
	v_mfma_f32_32x32x16_bf16 v[18:33], v[248:251], v[204:207], v[18:33]
	s_waitcnt lgkmcnt(0)
	v_mfma_f32_32x32x16_bf16 v[66:81], v[236:239], v[208:211], v[66:81]
	v_mfma_f32_32x32x16_bf16 v[2:17], v[248:251], v[208:211], v[2:17]
	s_cbranch_vccz .LBB0_1928
.LBB0_1935:
	s_cmpk_gt_u32 s4, 0x3bf
	s_cselect_b64 s[16:17], -1, 0
	s_and_b64 vcc, exec, s[16:17]
	s_waitcnt vmcnt(63) expcnt(7) lgkmcnt(15)
	s_barrier
	s_waitcnt vmcnt(11)
	ds_write_b128 v184, v[130:133]
	s_waitcnt vmcnt(10)
	ds_write_b128 v184, v[134:137] offset:4608
	s_waitcnt vmcnt(9)
	ds_write_b128 v184, v[138:141] offset:9216
	s_waitcnt vmcnt(8)
	ds_write_b128 v184, v[142:145] offset:13824
	s_waitcnt vmcnt(7)
	ds_write_b128 v184, v[146:149] offset:18432
	s_waitcnt vmcnt(6)
	ds_write_b128 v184, v[150:153] offset:23040
	s_waitcnt vmcnt(5)
	ds_write_b128 v184, v[154:157] offset:27648
	s_waitcnt vmcnt(4)
	ds_write_b128 v184, v[158:161] offset:32256
	s_waitcnt vmcnt(3)
	ds_write_b128 v184, v[162:165] offset:36864
	s_waitcnt vmcnt(2)
	ds_write_b128 v184, v[166:169] offset:41472
	s_waitcnt vmcnt(1)
	ds_write_b128 v184, v[170:173] offset:46080
	s_waitcnt vmcnt(0)
	ds_write_b128 v184, v[174:177] offset:50688
	s_waitcnt lgkmcnt(0)
	s_barrier
	ds_read_b128 v[188:191], v185
	ds_read_b128 v[192:195], v186 offset:18432
	ds_read_b128 v[244:247], v185 offset:4608
	ds_read_b128 v[200:203], v186 offset:23040
	ds_read_b128 v[204:207], v186 offset:27648
	ds_read_b128 v[208:211], v186 offset:32256
	s_cbranch_vccnz .LBB0_1934
	v_lshl_add_u64 v[138:139], v[180:181], 0, v[198:199]
	v_add_co_u32_e32 v134, vcc, 0x10000, v138
	v_lshl_add_u64 v[170:171], v[178:179], 0, v[198:199]
	s_nop 0
	v_addc_co_u32_e32 v135, vcc, 0, v139, vcc
	v_add_co_u32_e32 v140, vcc, 0x20000, v138
	global_load_dwordx4 v[130:133], v[138:139], off offset:128
	s_nop 0
	global_load_dwordx4 v[134:137], v[134:135], off offset:128
	v_addc_co_u32_e32 v141, vcc, 0, v139, vcc
	v_add_co_u32_e32 v142, vcc, 0x30000, v138
	s_nop 1
	v_addc_co_u32_e32 v143, vcc, 0, v139, vcc
	v_add_co_u32_e32 v146, vcc, 0xd150000, v170
	global_load_dwordx4 v[138:141], v[140:141], off offset:128
	s_nop 0
	global_load_dwordx4 v[142:145], v[142:143], off offset:128
	v_addc_co_u32_e32 v147, vcc, 0, v171, vcc
	v_add_co_u32_e32 v150, vcc, 0xd160000, v170
	s_nop 1
	v_addc_co_u32_e32 v151, vcc, 0, v171, vcc
	v_add_co_u32_e32 v154, vcc, 0xd170000, v170
	global_load_dwordx4 v[146:149], v[146:147], off offset:128
	s_nop 0
	global_load_dwordx4 v[150:153], v[150:151], off offset:128
	v_addc_co_u32_e32 v155, vcc, 0, v171, vcc
	v_add_co_u32_e32 v158, vcc, 0xd180000, v170
	s_nop 1
	v_addc_co_u32_e32 v159, vcc, 0, v171, vcc
	v_add_co_u32_e32 v162, vcc, 0xd190000, v170
	global_load_dwordx4 v[154:157], v[154:155], off offset:128
	s_nop 0
	global_load_dwordx4 v[158:161], v[158:159], off offset:128
	v_addc_co_u32_e32 v163, vcc, 0, v171, vcc
	v_add_co_u32_e32 v166, vcc, 0xd1a0000, v170
	s_nop 1
	v_addc_co_u32_e32 v167, vcc, 0, v171, vcc
	v_add_co_u32_e32 v172, vcc, 0xd1b0000, v170
	global_load_dwordx4 v[162:165], v[162:163], off offset:128
	s_nop 0
	global_load_dwordx4 v[166:169], v[166:167], off offset:128
	v_addc_co_u32_e32 v173, vcc, 0, v171, vcc
	v_add_co_u32_e32 v174, vcc, 0xd1c0000, v170
	s_nop 1
	v_addc_co_u32_e32 v175, vcc, 0, v171, vcc
	global_load_dwordx4 v[170:173], v[172:173], off offset:128
	s_nop 0
	global_load_dwordx4 v[174:177], v[174:175], off offset:128
	s_branch .LBB0_1934

; #define MFMA32(a, b, c) __builtin_amdgcn_mfma_f32_32x32x16_bf16((a), (b), (c), 0, 0, 0)
; DI void gemm_wide(f32x16 (&acc)[2][4], const u16* __restrict__ A, int lda, const u16* __restrict__ Bt, int ldb, int K,
;                   char* smem) {
;     ...
;   for (int k0 = 0; k0 < K; k0 += 64) {
;     __syncthreads();
; #pragma unroll
;     for (int i = 0; i < 4; ++i) *(u32x4*)(As + (lr + 32 * i) * LS + lk) = ra[i];
; #pragma unroll
;     for (int i = 0; i < 8; ++i) *(u32x4*)(Bs + (lr + 32 * i) * LS + lk) = rb[i];
;     __syncthreads();
;     if (k0 + 64 < K) {
;       const int k1 = k0 + 64 + lk;
; #pragma unroll
;       for (int i = 0; i < 4; ++i) ra[i] = *(const u32x4*)(A + (size_t)(lr + 32 * i) * lda + k1);
; #pragma unroll
;       for (int i = 0; i < 8; ++i) rb[i] = *(const u32x4*)(Bt + (size_t)(lr + 32 * i) * ldb + k1);
;     }
; #pragma unroll
;     for (int s = 0; s < 4; ++s) {
;       bf16x8 a[2], b[4];
; #pragma unroll
;       for (int i = 0; i < 2; ++i) a[i] = *(const bf16x8*)(As + (wm * 64 + i * 32 + l31) * LS + s * 16 + hh * 8);
; #pragma unroll
;       for (int j = 0; j < 4; ++j) b[j] = *(const bf16x8*)(Bs + (wn * 128 + j * 32 + l31) * LS + s * 16 + hh * 8);
; #pragma unroll
;       for (int i = 0; i < 2; ++i)
; #pragma unroll
;         for (int j = 0; j < 4; ++j) acc[i][j] = MFMA32(a[i], b[j], acc[i][j]);
;     }
;   }
.LBB0_1959:
	s_add_i32 s2, s2, 64
	v_lshl_add_u64 v[178:179], v[178:179], 0, s[50:51]
	v_lshl_add_u64 v[180:181], v[180:181], 0, s[50:51]
	s_andn2_b64 vcc, exec, s[16:17]
	ds_read_b128 v[236:239], v185 offset:32
	ds_read_b128 v[224:227], v186 offset:18464
	ds_read_b128 v[248:251], v185 offset:4640
	ds_read_b128 v[230:233], v186 offset:23072
	s_waitcnt lgkmcnt(8)
	v_mfma_f32_32x32x16_bf16 v[114:129], v[188:191], v[192:195], v[114:129]
	s_waitcnt lgkmcnt(7)
	v_mfma_f32_32x32x16_bf16 v[50:65], v[244:247], v[192:195], v[50:65]
	ds_read_b128 v[192:195], v186 offset:27680
	s_waitcnt lgkmcnt(7)
	v_mfma_f32_32x32x16_bf16 v[98:113], v[188:191], v[200:203], v[98:113]
	v_mfma_f32_32x32x16_bf16 v[34:49], v[244:247], v[200:203], v[34:49]
	ds_read_b128 v[200:203], v186 offset:32288
	s_waitcnt lgkmcnt(7)
	v_mfma_f32_32x32x16_bf16 v[82:97], v[188:191], v[204:207], v[82:97]
	v_mfma_f32_32x32x16_bf16 v[18:33], v[244:247], v[204:207], v[18:33]
	s_waitcnt lgkmcnt(6)
	v_mfma_f32_32x32x16_bf16 v[66:81], v[188:191], v[208:211], v[66:81]
	v_mfma_f32_32x32x16_bf16 v[2:17], v[244:247], v[208:211], v[2:17]
	ds_read_b128 v[188:191], v185 offset:64
	ds_read_b128 v[204:207], v186 offset:18496
	ds_read_b128 v[244:247], v185 offset:4672
	ds_read_b128 v[208:211], v186 offset:23104
	s_waitcnt lgkmcnt(8)
	v_mfma_f32_32x32x16_bf16 v[114:129], v[236:239], v[224:227], v[114:129]
	s_waitcnt lgkmcnt(7)
	v_mfma_f32_32x32x16_bf16 v[50:65], v[248:251], v[224:227], v[50:65]
	ds_read_b128 v[224:227], v186 offset:27712
	s_waitcnt lgkmcnt(7)
	v_mfma_f32_32x32x16_bf16 v[98:113], v[236:239], v[230:233], v[98:113]
	v_mfma_f32_32x32x16_bf16 v[34:49], v[248:251], v[230:233], v[34:49]
	ds_read_b128 v[230:233], v186 offset:32320
	s_waitcnt lgkmcnt(7)
	v_mfma_f32_32x32x16_bf16 v[82:97], v[236:239], v[192:195], v[82:97]
	v_mfma_f32_32x32x16_bf16 v[18:33], v[248:251], v[192:195], v[18:33]
	s_waitcnt lgkmcnt(6)
	v_mfma_f32_32x32x16_bf16 v[66:81], v[236:239], v[200:203], v[66:81]
	v_mfma_f32_32x32x16_bf16 v[2:17], v[248:251], v[200:203], v[2:17]
	ds_read_b128 v[236:239], v185 offset:96
	ds_read_b128 v[192:195], v186 offset:18528
	ds_read_b128 v[248:251], v185 offset:4704
	ds_read_b128 v[200:203], v186 offset:23136
	s_waitcnt lgkmcnt(8)
	v_mfma_f32_32x32x16_bf16 v[114:129], v[188:191], v[204:207], v[114:129]
	s_waitcnt lgkmcnt(7)
	v_mfma_f32_32x32x16_bf16 v[50:65], v[244:247], v[204:207], v[50:65]
	ds_read_b128 v[204:207], v186 offset:27744
	s_waitcnt lgkmcnt(7)
	v_mfma_f32_32x32x16_bf16 v[98:113], v[188:191], v[208:211], v[98:113]
	v_mfma_f32_32x32x16_bf16 v[34:49], v[244:247], v[208:211], v[34:49]
	ds_read_b128 v[208:211], v186 offset:32352
	s_waitcnt lgkmcnt(7)
	v_mfma_f32_32x32x16_bf16 v[82:97], v[188:191], v[224:227], v[82:97]
	v_mfma_f32_32x32x16_bf16 v[18:33], v[244:247], v[224:227], v[18:33]
	s_waitcnt lgkmcnt(6)
	v_mfma_f32_32x32x16_bf16 v[66:81], v[188:191], v[230:233], v[66:81]
	v_mfma_f32_32x32x16_bf16 v[2:17], v[244:247], v[230:233], v[2:17]
	s_waitcnt lgkmcnt(4)
	v_mfma_f32_32x32x16_bf16 v[114:129], v[236:239], v[192:195], v[114:129]
	s_waitcnt lgkmcnt(3)
	v_mfma_f32_32x32x16_bf16 v[50:65], v[248:251], v[192:195], v[50:65]
	s_waitcnt lgkmcnt(2)
	v_mfma_f32_32x32x16_bf16 v[98:113], v[236:239], v[200:203], v[98:113]
	v_mfma_f32_32x32x16_bf16 v[34:49], v[248:251], v[200:203], v[34:49]
	s_waitcnt lgkmcnt(1)
	v_mfma_f32_32x32x16_bf16 v[82:97], v[236:239], v[204:207], v[82:97]
	v_mfma_f32_32x32x16_bf16 v[18:33], v[248:251], v[204:207], v[18:33]
	s_waitcnt lgkmcnt(0)
	v_mfma_f32_32x32x16_bf16 v[66:81], v[236:239], v[208:211], v[66:81]
	v_mfma_f32_32x32x16_bf16 v[2:17], v[248:251], v[208:211], v[2:17]
	s_cbranch_vccz .LBB0_1945
.LBB0_1960:
	s_cmpk_gt_u32 s2, 0x3bf
	s_cselect_b64 s[16:17], -1, 0
	s_and_b64 vcc, exec, s[16:17]
	s_waitcnt vmcnt(63) expcnt(7) lgkmcnt(15)
	s_barrier
	s_waitcnt vmcnt(11)
	ds_write_b128 v184, v[130:133]
	s_waitcnt vmcnt(10)
	ds_write_b128 v184, v[134:137] offset:4608
	s_waitcnt vmcnt(9)
	ds_write_b128 v184, v[138:141] offset:9216
	s_waitcnt vmcnt(8)
	ds_write_b128 v184, v[142:145] offset:13824
	s_waitcnt vmcnt(7)
	ds_write_b128 v184, v[146:149] offset:18432
	s_waitcnt vmcnt(6)
	ds_write_b128 v184, v[150:153] offset:23040
	s_waitcnt vmcnt(5)
	ds_write_b128 v184, v[154:157] offset:27648
	s_waitcnt vmcnt(4)
	ds_write_b128 v184, v[158:161] offset:32256
	s_waitcnt vmcnt(3)
	ds_write_b128 v184, v[162:165] offset:36864
	s_waitcnt vmcnt(2)
	ds_write_b128 v184, v[166:169] offset:41472
	s_waitcnt vmcnt(1)
	ds_write_b128 v184, v[170:173] offset:46080
	s_waitcnt vmcnt(0)
	ds_write_b128 v184, v[174:177] offset:50688
	s_waitcnt lgkmcnt(0)
	s_barrier
	ds_read_b128 v[188:191], v185
	ds_read_b128 v[192:195], v186 offset:18432
	ds_read_b128 v[244:247], v185 offset:4608
	ds_read_b128 v[200:203], v186 offset:23040
	ds_read_b128 v[204:207], v186 offset:27648
	ds_read_b128 v[208:211], v186 offset:32256
	s_cbranch_vccnz .LBB0_1959
	v_lshl_add_u64 v[138:139], v[180:181], 0, v[198:199]
	v_add_co_u32_e32 v134, vcc, 0x10000, v138
	v_lshl_add_u64 v[170:171], v[178:179], 0, v[198:199]
	s_nop 0
	v_addc_co_u32_e32 v135, vcc, 0, v139, vcc
	v_add_co_u32_e32 v140, vcc, 0x20000, v138
	global_load_dwordx4 v[130:133], v[138:139], off offset:128
	s_nop 0
	global_load_dwordx4 v[134:137], v[134:135], off offset:128
	v_addc_co_u32_e32 v141, vcc, 0, v139, vcc
	v_add_co_u32_e32 v142, vcc, 0x30000, v138
	s_nop 1
	v_addc_co_u32_e32 v143, vcc, 0, v139, vcc
	v_add_co_u32_e32 v146, vcc, 0xd150000, v170
	global_load_dwordx4 v[138:141], v[140:141], off offset:128
	s_nop 0
	global_load_dwordx4 v[142:145], v[142:143], off offset:128
	v_addc_co_u32_e32 v147, vcc, 0, v171, vcc
	v_add_co_u32_e32 v150, vcc, 0xd160000, v170
	s_nop 1
	v_addc_co_u32_e32 v151, vcc, 0, v171, vcc
	v_add_co_u32_e32 v154, vcc, 0xd170000, v170
	global_load_dwordx4 v[146:149], v[146:147], off offset:128
	s_nop 0
	global_load_dwordx4 v[150:153], v[150:151], off offset:128
	v_addc_co_u32_e32 v155, vcc, 0, v171, vcc
	v_add_co_u32_e32 v158, vcc, 0xd180000, v170
	s_nop 1
	v_addc_co_u32_e32 v159, vcc, 0, v171, vcc
	v_add_co_u32_e32 v162, vcc, 0xd190000, v170
	global_load_dwordx4 v[154:157], v[154:155], off offset:128
	s_nop 0
	global_load_dwordx4 v[158:161], v[158:159], off offset:128
	v_addc_co_u32_e32 v163, vcc, 0, v171, vcc
	v_add_co_u32_e32 v166, vcc, 0xd1a0000, v170
	s_nop 1
	v_addc_co_u32_e32 v167, vcc, 0, v171, vcc
	v_add_co_u32_e32 v172, vcc, 0xd1b0000, v170
	global_load_dwordx4 v[162:165], v[162:163], off offset:128
	s_nop 0
	global_load_dwordx4 v[166:169], v[166:167], off offset:128
	v_addc_co_u32_e32 v173, vcc, 0, v171, vcc
	v_add_co_u32_e32 v174, vcc, 0xd1c0000, v170
	s_nop 1
	v_addc_co_u32_e32 v175, vcc, 0, v171, vcc
	global_load_dwordx4 v[170:173], v[172:173], off offset:128
	s_nop 0
	global_load_dwordx4 v[174:177], v[174:175], off offset:128
	s_branch .LBB0_1959

; #define MFMA32(a, b, c) __builtin_amdgcn_mfma_f32_32x32x16_bf16((a), (b), (c), 0, 0, 0)
; DI void gemm_wide(f32x16 (&acc)[2][4], const u16* __restrict__ A, int lda, const u16* __restrict__ Bt, int ldb, int K,
;                   char* smem) {
;     ...
;   for (int k0 = 0; k0 < K; k0 += 64) {
;     __syncthreads();
; #pragma unroll
;     for (int i = 0; i < 4; ++i) *(u32x4*)(As + (lr + 32 * i) * LS + lk) = ra[i];
; #pragma unroll
;     for (int i = 0; i < 8; ++i) *(u32x4*)(Bs + (lr + 32 * i) * LS + lk) = rb[i];
;     __syncthreads();
;     if (k0 + 64 < K) {
;       const int k1 = k0 + 64 + lk;
; #pragma unroll
;       for (int i = 0; i < 4; ++i) ra[i] = *(const u32x4*)(A + (size_t)(lr + 32 * i) * lda + k1);
; #pragma unroll
;       for (int i = 0; i < 8; ++i) rb[i] = *(const u32x4*)(Bt + (size_t)(lr + 32 * i) * ldb + k1);
;     }
; #pragma unroll
;     for (int s = 0; s < 4; ++s) {
;       bf16x8 a[2], b[4];
; #pragma unroll
;       for (int i = 0; i < 2; ++i) a[i] = *(const bf16x8*)(As + (wm * 64 + i * 32 + l31) * LS + s * 16 + hh * 8);
; #pragma unroll
;       for (int j = 0; j < 4; ++j) b[j] = *(const bf16x8*)(Bs + (wn * 128 + j * 32 + l31) * LS + s * 16 + hh * 8);
; #pragma unroll
;       for (int i = 0; i < 2; ++i)
; #pragma unroll
;         for (int j = 0; j < 4; ++j) acc[i][j] = MFMA32(a[i], b[j], acc[i][j]);
;     }
;   }
.LBB0_2018:
	s_add_i32 s5, s5, 64
	v_lshl_add_u64 v[178:179], v[178:179], 0, s[50:51]
	v_lshl_add_u64 v[180:181], v[180:181], 0, s[50:51]
	s_andn2_b64 vcc, exec, s[12:13]
	ds_read_b128 v[236:239], v185 offset:32
	ds_read_b128 v[224:227], v186 offset:18464
	ds_read_b128 v[248:251], v185 offset:4640
	ds_read_b128 v[230:233], v186 offset:23072
	s_waitcnt lgkmcnt(8)
	v_mfma_f32_32x32x16_bf16 v[114:129], v[188:191], v[192:195], v[114:129]
	s_waitcnt lgkmcnt(7)
	v_mfma_f32_32x32x16_bf16 v[50:65], v[244:247], v[192:195], v[50:65]
	ds_read_b128 v[192:195], v186 offset:27680
	s_waitcnt lgkmcnt(7)
	v_mfma_f32_32x32x16_bf16 v[98:113], v[188:191], v[200:203], v[98:113]
	v_mfma_f32_32x32x16_bf16 v[34:49], v[244:247], v[200:203], v[34:49]
	ds_read_b128 v[200:203], v186 offset:32288
	s_waitcnt lgkmcnt(7)
	v_mfma_f32_32x32x16_bf16 v[82:97], v[188:191], v[204:207], v[82:97]
	v_mfma_f32_32x32x16_bf16 v[18:33], v[244:247], v[204:207], v[18:33]
	s_waitcnt lgkmcnt(6)
	v_mfma_f32_32x32x16_bf16 v[66:81], v[188:191], v[208:211], v[66:81]
	v_mfma_f32_32x32x16_bf16 v[2:17], v[244:247], v[208:211], v[2:17]
	ds_read_b128 v[188:191], v185 offset:64
	ds_read_b128 v[204:207], v186 offset:18496
	ds_read_b128 v[244:247], v185 offset:4672
	ds_read_b128 v[208:211], v186 offset:23104
	s_waitcnt lgkmcnt(8)
	v_mfma_f32_32x32x16_bf16 v[114:129], v[236:239], v[224:227], v[114:129]
	s_waitcnt lgkmcnt(7)
	v_mfma_f32_32x32x16_bf16 v[50:65], v[248:251], v[224:227], v[50:65]
	ds_read_b128 v[224:227], v186 offset:27712
	s_waitcnt lgkmcnt(7)
	v_mfma_f32_32x32x16_bf16 v[98:113], v[236:239], v[230:233], v[98:113]
	v_mfma_f32_32x32x16_bf16 v[34:49], v[248:251], v[230:233], v[34:49]
	ds_read_b128 v[230:233], v186 offset:32320
	s_waitcnt lgkmcnt(7)
	v_mfma_f32_32x32x16_bf16 v[82:97], v[236:239], v[192:195], v[82:97]
	v_mfma_f32_32x32x16_bf16 v[18:33], v[248:251], v[192:195], v[18:33]
	s_waitcnt lgkmcnt(6)
	v_mfma_f32_32x32x16_bf16 v[66:81], v[236:239], v[200:203], v[66:81]
	v_mfma_f32_32x32x16_bf16 v[2:17], v[248:251], v[200:203], v[2:17]
	ds_read_b128 v[236:239], v185 offset:96
	ds_read_b128 v[192:195], v186 offset:18528
	ds_read_b128 v[248:251], v185 offset:4704
	ds_read_b128 v[200:203], v186 offset:23136
	s_waitcnt lgkmcnt(8)
	v_mfma_f32_32x32x16_bf16 v[114:129], v[188:191], v[204:207], v[114:129]
	s_waitcnt lgkmcnt(7)
	v_mfma_f32_32x32x16_bf16 v[50:65], v[244:247], v[204:207], v[50:65]
	ds_read_b128 v[204:207], v186 offset:27744
	s_waitcnt lgkmcnt(7)
	v_mfma_f32_32x32x16_bf16 v[98:113], v[188:191], v[208:211], v[98:113]
	v_mfma_f32_32x32x16_bf16 v[34:49], v[244:247], v[208:211], v[34:49]
	ds_read_b128 v[208:211], v186 offset:32352
	s_waitcnt lgkmcnt(7)
	v_mfma_f32_32x32x16_bf16 v[82:97], v[188:191], v[224:227], v[82:97]
	v_mfma_f32_32x32x16_bf16 v[18:33], v[244:247], v[224:227], v[18:33]
	s_waitcnt lgkmcnt(6)
	v_mfma_f32_32x32x16_bf16 v[66:81], v[188:191], v[230:233], v[66:81]
	v_mfma_f32_32x32x16_bf16 v[2:17], v[244:247], v[230:233], v[2:17]
	s_waitcnt lgkmcnt(4)
	v_mfma_f32_32x32x16_bf16 v[114:129], v[236:239], v[192:195], v[114:129]
	s_waitcnt lgkmcnt(3)
	v_mfma_f32_32x32x16_bf16 v[50:65], v[248:251], v[192:195], v[50:65]
	s_waitcnt lgkmcnt(2)
	v_mfma_f32_32x32x16_bf16 v[98:113], v[236:239], v[200:203], v[98:113]
	v_mfma_f32_32x32x16_bf16 v[34:49], v[248:251], v[200:203], v[34:49]
	s_waitcnt lgkmcnt(1)
	v_mfma_f32_32x32x16_bf16 v[82:97], v[236:239], v[204:207], v[82:97]
	v_mfma_f32_32x32x16_bf16 v[18:33], v[248:251], v[204:207], v[18:33]
	s_waitcnt lgkmcnt(0)
	v_mfma_f32_32x32x16_bf16 v[66:81], v[236:239], v[208:211], v[66:81]
	v_mfma_f32_32x32x16_bf16 v[2:17], v[248:251], v[208:211], v[2:17]
	s_cbranch_vccz .LBB0_2005
.LBB0_2019:
	s_cmpk_gt_u32 s5, 0xabf
	s_cselect_b64 s[12:13], -1, 0
	s_and_b64 vcc, exec, s[12:13]
	s_waitcnt lgkmcnt(0)
	s_barrier
	s_waitcnt vmcnt(11)
	ds_write_b128 v184, v[130:133]
	s_waitcnt vmcnt(10)
	ds_write_b128 v184, v[134:137] offset:4608
	s_waitcnt vmcnt(9)
	ds_write_b128 v184, v[138:141] offset:9216
	s_waitcnt vmcnt(8)
	ds_write_b128 v184, v[142:145] offset:13824
	s_waitcnt vmcnt(7)
	ds_write_b128 v184, v[146:149] offset:18432
	s_waitcnt vmcnt(6)
	ds_write_b128 v184, v[150:153] offset:23040
	s_waitcnt vmcnt(5)
	ds_write_b128 v184, v[154:157] offset:27648
	s_waitcnt vmcnt(4)
	ds_write_b128 v184, v[158:161] offset:32256
	s_waitcnt vmcnt(3)
	ds_write_b128 v184, v[162:165] offset:36864
	s_waitcnt vmcnt(2)
	ds_write_b128 v184, v[166:169] offset:41472
	s_waitcnt vmcnt(1)
	ds_write_b128 v184, v[170:173] offset:46080
	s_waitcnt vmcnt(0)
	ds_write_b128 v184, v[174:177] offset:50688
	s_waitcnt lgkmcnt(0)
	s_barrier
	ds_read_b128 v[188:191], v185
	ds_read_b128 v[192:195], v186 offset:18432
	ds_read_b128 v[244:247], v185 offset:4608
	ds_read_b128 v[200:203], v186 offset:23040
	ds_read_b128 v[204:207], v186 offset:27648
	ds_read_b128 v[208:211], v186 offset:32256
	s_cbranch_vccnz .LBB0_2018
	v_lshl_add_u64 v[138:139], v[180:181], 0, v[198:199]
	v_add_co_u32_e32 v130, vcc, 0x2200000, v138
	v_lshl_add_u64 v[170:171], v[178:179], 0, v[198:199]
	s_nop 0
	v_addc_co_u32_e32 v131, vcc, 0, v139, vcc
	v_add_co_u32_e32 v134, vcc, 0x222c000, v138
	s_mov_b32 s14, 0xdc50000
	s_nop 0
	v_addc_co_u32_e32 v135, vcc, 0, v139, vcc
	v_add_co_u32_e32 v140, vcc, 0x2258000, v138
	global_load_dwordx4 v[130:133], v[130:131], off offset:128
	s_nop 0
	global_load_dwordx4 v[134:137], v[134:135], off offset:128
	v_addc_co_u32_e32 v141, vcc, 0, v139, vcc
	v_add_co_u32_e32 v142, vcc, 0x2284000, v138
	s_nop 1
	v_addc_co_u32_e32 v143, vcc, 0, v139, vcc
	v_add_co_u32_e32 v146, vcc, s14, v170
	s_mov_b32 s14, 0xdc7c000
	s_nop 0
	v_addc_co_u32_e32 v147, vcc, 0, v171, vcc
	v_add_co_u32_e32 v150, vcc, s14, v170
	global_load_dwordx4 v[138:141], v[140:141], off offset:128
	s_nop 0
	global_load_dwordx4 v[142:145], v[142:143], off offset:128
	v_addc_co_u32_e32 v151, vcc, 0, v171, vcc
	v_add_co_u32_e32 v154, vcc, 0xdca8000, v170
	global_load_dwordx4 v[146:149], v[146:147], off offset:128
	s_nop 0
	global_load_dwordx4 v[150:153], v[150:151], off offset:128
	v_addc_co_u32_e32 v155, vcc, 0, v171, vcc
	v_add_co_u32_e32 v158, vcc, 0xdcd4000, v170
	s_nop 1
	v_addc_co_u32_e32 v159, vcc, 0, v171, vcc
	v_add_co_u32_e32 v162, vcc, 0xdd00000, v170
	global_load_dwordx4 v[154:157], v[154:155], off offset:128
	s_nop 0
	global_load_dwordx4 v[158:161], v[158:159], off offset:128
	v_addc_co_u32_e32 v163, vcc, 0, v171, vcc
	v_add_co_u32_e32 v166, vcc, 0xdd2c000, v170
	s_nop 1
	v_addc_co_u32_e32 v167, vcc, 0, v171, vcc
	v_add_co_u32_e32 v172, vcc, 0xdd58000, v170
	global_load_dwordx4 v[162:165], v[162:163], off offset:128
	s_nop 0
	global_load_dwordx4 v[166:169], v[166:167], off offset:128
	v_addc_co_u32_e32 v173, vcc, 0, v171, vcc
	v_add_co_u32_e32 v174, vcc, 0xdd84000, v170
	s_nop 1
	v_addc_co_u32_e32 v175, vcc, 0, v171, vcc
	global_load_dwordx4 v[170:173], v[172:173], off offset:128
	s_nop 0
	global_load_dwordx4 v[174:177], v[174:175], off offset:128
	s_branch .LBB0_2018
